# attention modes D/A/C: rescale check reduced to one compare against a per-lane threshold register; accumulator-init copies removed (constant reference fed as MFMA C operand)
# speedup vs baseline: 1.0425x; 1.0035x over previous
; template <int MODE>
; DI void attn_tile(const Params& p, int layer, int tile, char* smem) {
;     ...
;   if (MODE == 3) {
;     bf16x8 x1 = qf[NKQ - 2], x2 = qf[NKQ - 1];
;     const f32x4* rt = (const f32x4*)(p.ws + OFF_ROPE) + (size_t)qpos * 8 + 4 * h;
; #pragma unroll
;     for (int j2 = 0; j2 < 4; ++j2) {
;       const f32x4 cs4 = rt[j2];
; #pragma unroll
;       for (int e = 0; e < 2; ++e) {
;         const int j = 2 * j2 + e;
;         const float c = cs4[2 * e], sn = cs4[2 * e + 1];
;         float a = __uint_as_float(((unsigned)(u16)x1[j]) << 16), b = __uint_as_float(((unsigned)(u16)x2[j]) << 16);
;         unsigned w = pack2(a * c - b * sn, a * sn + b * c);
;         x1[j] = (short)(w & 0xffff); x2[j] = (short)(w >> 16);
;       }
;     }
;     qf[NKQ - 2] = x1; qf[NKQ - 1] = x2;
;   }
;   u32x4 rk0[KLD], rv0, rk1[KLD], rv1;
;   const u16* Kt = Kp + tok0 * ldk;
;   const u16* Vt = Vp + tok0 * ldv;
;   unsigned koff[KLD];
; #pragma unroll
;   for (int pp = 0; pp < KLD; ++pp) { int c = tid + NTHR * pp; if (c >= 64 * KCH) c = tid; const int row = c / KCH, col = c % KCH; koff[pp] = (unsigned)row * ldk + col * 8; }
;   const unsigned voff = (unsigned)(tid >> 3) * ldv + (tid & 7) * 8;
;   const int ktl = kt1 - 1;
;   auto gload = [&](u32x4 (&rk)[KLD], u32x4& rv, int kt) {
;     kt = kt < ktl ? kt : ktl;
; #pragma unroll
;     for (int pp = 0; pp < KLD; ++pp) rk[pp] = *(const u32x4*)(Kt + (koff[pp] + (unsigned)(kt * 64) * ldk));
;     rv = *(const u32x4*)(Vt + (voff + (unsigned)(kt * 64) * ldv));
;   };
;   auto lstore = [&](u32x4 (&rk)[KLD], u32x4& rv, int buf) {
; #pragma unroll
;     for (int pp = 0; pp < KLD; ++pp) { const int c = tid + NTHR * pp; if (c < 64 * KCH) { const int row = c / KCH, col = c % KCH; *(u32x4*)(Ks + (buf * 64 + row) * KROW + col * 8) = rk[pp]; } }
;     *(u32x4*)(Vs + (buf * 64 + (tid >> 3)) * VROW + (tid & 7) * 8) = rv;
;   };
;   f32x16 o0, o1, negm;
; #pragma unroll
;   for (int i = 0; i < 16; ++i) { o0[i] = 0.f; o1[i] = 0.f; negm[i] = 0.f; }
;   float mref = 0.f, lsum = 0.f;
;   bool started = false;
;   int qr = 0, qc = 0, cs = 0, rs = 0;
;   if (MODE == 2) { qr = qpos >> 6; qc = qpos & 63; cs = qc - 8; cs = cs < 0 ? 0 : (cs > 48 ? 48 : cs); rs = qr - 4; rs = rs < 0 ? 0 : (rs > 56 ? 56 : rs); }
;   const int i16 = lane & 15, qq = i16 >> 2, pp4 = i16 & 3, g16 = (lane >> 4) & 1;
.LBB0_114:
	s_or_b64 exec, exec, s[0:1]
	s_waitcnt vmcnt(4)
	v_lshlrev_b32_e32 v30, 16, v6
	v_lshlrev_b32_e32 v0, 16, v2
	v_pk_mul_f32 v[30:31], v[26:27], v[30:31] op_sel:[1,0] op_sel_hi:[0,0]
	v_pk_fma_f32 v[32:33], v[26:27], v[0:1], v[30:31] neg_lo:[0,0,1] neg_hi:[0,0,1]
	v_pk_fma_f32 v[26:27], v[26:27], v[0:1], v[30:31] op_sel_hi:[1,0,1]
	v_and_b32_e32 v0, 0xffff0000, v2
	v_and_b32_e32 v2, 0xffff0000, v6
	v_cvt_pk_bf16_f32 v32, v32, v27
	v_pk_mul_f32 v[26:27], v[28:29], v[2:3] op_sel:[1,0] op_sel_hi:[0,0]
	v_pk_fma_f32 v[30:31], v[28:29], v[0:1], v[26:27] neg_lo:[0,0,1] neg_hi:[0,0,1]
	v_pk_fma_f32 v[26:27], v[28:29], v[0:1], v[26:27] op_sel_hi:[1,0,1]
	v_lshlrev_b32_e32 v2, 16, v7
	v_cvt_pk_bf16_f32 v6, v30, v27
	v_lshlrev_b32_e32 v0, 16, v3
	v_pk_mul_f32 v[26:27], v[22:23], v[2:3] op_sel:[1,0] op_sel_hi:[0,0]
	v_and_b32_e32 v2, 0xffff0000, v7
	s_mov_b32 s0, 0x5040100
	v_pk_fma_f32 v[28:29], v[22:23], v[0:1], v[26:27] neg_lo:[0,0,1] neg_hi:[0,0,1]
	v_pk_fma_f32 v[22:23], v[22:23], v[0:1], v[26:27] op_sel_hi:[1,0,1]
	s_mov_b32 s1, 0x7060302
	v_and_b32_e32 v0, 0xffff0000, v3
	v_pk_mul_f32 v[2:3], v[24:25], v[2:3] op_sel:[1,0] op_sel_hi:[0,0]
	v_perm_b32 v126, v6, v32, s0
	v_perm_b32 v130, v6, v32, s1
	v_pk_fma_f32 v[6:7], v[24:25], v[0:1], v[2:3] neg_lo:[0,0,1] neg_hi:[0,0,1]
	v_pk_fma_f32 v[2:3], v[24:25], v[0:1], v[2:3] op_sel_hi:[1,0,1]
	v_cvt_pk_bf16_f32 v22, v28, v23
	v_cvt_pk_bf16_f32 v0, v6, v3
	v_perm_b32 v127, v0, v22, s0
	v_perm_b32 v131, v0, v22, s1
	v_lshlrev_b32_e32 v0, 16, v8
	v_pk_mul_f32 v[6:7], v[14:15], v[0:1] op_sel:[1,0] op_sel_hi:[0,0]
	v_add_u32_e32 v0, 0xc000, v182
	v_lshl_add_u64 v[24:25], v[0:1], 1, s[14:15]
	v_add_u32_e32 v0, 0xc000, v184
	v_lshl_add_u64 v[26:27], v[0:1], 1, s[14:15]
	v_add_u32_e32 v0, 0x8000, v186
	global_load_dwordx4 v[138:141], v[24:25], off
	global_load_dwordx4 v[142:145], v[26:27], off
	v_lshl_add_u64 v[24:25], v[0:1], 1, s[16:17]
	global_load_dwordx4 v[134:137], v[24:25], off
	v_lshlrev_b32_e32 v2, 16, v4
	v_pk_fma_f32 v[22:23], v[14:15], v[2:3], v[6:7] neg_lo:[0,0,1] neg_hi:[0,0,1]
	v_pk_fma_f32 v[2:3], v[14:15], v[2:3], v[6:7] op_sel_hi:[1,0,1]
	v_and_b32_e32 v0, 0xffff0000, v4
	v_and_b32_e32 v2, 0xffff0000, v8
	v_cvt_pk_bf16_f32 v14, v22, v3
	v_pk_mul_f32 v[2:3], v[16:17], v[2:3] op_sel:[1,0] op_sel_hi:[0,0]
	v_pk_fma_f32 v[6:7], v[16:17], v[0:1], v[2:3] neg_lo:[0,0,1] neg_hi:[0,0,1]
	v_pk_fma_f32 v[2:3], v[16:17], v[0:1], v[2:3] op_sel_hi:[1,0,1]
	v_lshlrev_b32_e32 v185, 2, v39
	v_cvt_pk_bf16_f32 v0, v6, v3
	v_lshlrev_b32_e32 v2, 16, v9
	v_perm_b32 v128, v0, v14, s0
	v_perm_b32 v132, v0, v14, s1
	v_lshlrev_b32_e32 v0, 16, v5
	v_pk_mul_f32 v[2:3], v[10:11], v[2:3] op_sel:[1,0] op_sel_hi:[0,0]
	v_pk_fma_f32 v[6:7], v[10:11], v[0:1], v[2:3] neg_lo:[0,0,1] neg_hi:[0,0,1]
	v_pk_fma_f32 v[2:3], v[10:11], v[0:1], v[2:3] op_sel_hi:[1,0,1]
	v_and_b32_e32 v0, 0xffff0000, v5
	v_and_b32_e32 v2, 0xffff0000, v9
	v_cvt_pk_bf16_f32 v6, v6, v3
	v_pk_mul_f32 v[2:3], v[12:13], v[2:3] op_sel:[1,0] op_sel_hi:[0,0]
	v_pk_fma_f32 v[4:5], v[12:13], v[0:1], v[2:3] neg_lo:[0,0,1] neg_hi:[0,0,1]
	v_pk_fma_f32 v[2:3], v[12:13], v[0:1], v[2:3] op_sel_hi:[1,0,1]
	v_lshlrev_b32_e32 v40, 3, v39
	v_cvt_pk_bf16_f32 v0, v4, v3
	v_perm_b32 v129, v0, v6, s0
	v_perm_b32 v133, v0, v6, s1
	v_lshrrev_b32_e32 v0, 2, v34
	v_and_b32_e32 v2, 16, v34
	v_and_or_b32 v0, v0, 3, v185
	v_and_b32_e32 v4, 24, v35
	v_mul_lo_u32 v3, v36, s87
	v_lshl_or_b32 v2, v2, 1, v4
	v_mul_u32_u24_e32 v0, 0x48, v0
	v_lshl_add_u32 v190, v189, 1, v3
	v_mul_u32_u24_e32 v3, 0x68, v179
	v_lshl_add_u32 v191, v0, 1, v2
	v_lshlrev_b32_e32 v0, 1, v40
	v_lshl_add_u32 v192, v3, 1, v0
	v_lshlrev_b32_e32 v0, 1, v38
	v_mov_b32_e32 v14, v1
	v_mov_b32_e32 v15, v1
	s_waitcnt vmcnt(6)
	ds_write_b128 v190, v[18:21] offset:26624
	v_lshl_add_u32 v193, v37, 1, v0
	v_mov_b32_e32 v0, v1
	v_mov_b32_e32 v2, v1
	v_mov_b32_e32 v3, v1
	v_mov_b32_e32 v4, v1
	v_mov_b32_e32 v5, v1
	v_mov_b32_e32 v6, v1
	v_mov_b32_e32 v7, v1
	v_mov_b32_e32 v8, v1
	v_mov_b32_e32 v9, v1
	v_mov_b32_e32 v10, v1
	v_mov_b32_e32 v11, v1
	v_mov_b32_e32 v12, v1
	v_mov_b32_e32 v13, v1
	v_mov_b64_e32 v[32:33], v[14:15]
	v_mov_b32_e32 v210, 0
	v_mov_b64_e32 v[30:31], v[12:13]
	v_mov_b64_e32 v[28:29], v[10:11]
	v_mov_b64_e32 v[26:27], v[8:9]
	v_mov_b64_e32 v[24:25], v[6:7]
	v_mov_b64_e32 v[22:23], v[4:5]
	v_mov_b64_e32 v[20:21], v[2:3]
	v_mov_b64_e32 v[18:19], v[0:1]
	v_mov_b64_e32 v[16:17], v[14:15]
	v_and_b32_e32 v183, 63, v34
	s_lshl_b32 s20, s19, 6
	v_mov_b32_e32 v211, 0
	v_mov_b32_e32 v234, 0xefa18f08
	s_mov_b32 s21, -2
	v_mov_b32_e32 v212, 0
	v_mov_b64_e32 v[14:15], v[12:13]
	v_mov_b64_e32 v[12:13], v[10:11]
	v_mov_b64_e32 v[10:11], v[8:9]
	v_mov_b64_e32 v[8:9], v[6:7]
	v_mov_b64_e32 v[6:7], v[4:5]
	v_mov_b64_e32 v[4:5], v[2:3]
	v_mov_b64_e32 v[2:3], v[0:1]
	v_mov_b32_e32 v34, 0
	v_mov_b32_e32 v35, v210
	v_mov_b32_e32 v36, v210
	v_mov_b32_e32 v37, v210
	v_mov_b32_e32 v38, v210
	v_mov_b32_e32 v39, v210
	v_mov_b32_e32 v40, v210
	v_mov_b32_e32 v41, v210
	v_mov_b32_e32 v42, v210
	v_mov_b32_e32 v43, v210
	v_mov_b32_e32 v44, v210
	v_mov_b32_e32 v45, v210
	v_mov_b32_e32 v46, v210
	v_mov_b32_e32 v47, v210
	v_mov_b32_e32 v48, v210
	v_mov_b32_e32 v49, v210
	s_waitcnt lgkmcnt(0)
	s_barrier
	s_branch .LBB0_116

; DI f32x16 mfma(bf16x8 a, bf16x8 b, f32x16 c) { return __builtin_amdgcn_mfma_f32_32x32x16_bf16(a, b, c, 0, 0, 0); }
; DI float fexp2(float x) { return __builtin_amdgcn_exp2f(x); }
; template <int MODE>
; DI void attn_tile(const Params& p, int layer, int tile, char* smem) {
;     ...
;       f32x16 s0 = negm, s1 = negm;
; #pragma unroll
;       for (int d0 = 0; d0 < NKQ; ++d0) {
;         bf16x8 k0 = *(const bf16x8*)(Kb + d0 * 16);
;         bf16x8 k1 = *(const bf16x8*)(Kb + 32 * KROW + d0 * 16);
;         s0 = mfma(k0, qf[d0], s0);
;         s1 = mfma(k1, qf[d0], s1);
;       }
;       if (MODE == 0) {
;         const float* tb = tbl + (kt * 64 + 4 * h - qpos + 1280);
; #pragma unroll
;         for (int i = 0; i < 16; ++i) { s0[i] += tb[(i & 3) + 8 * (i >> 2)]; s1[i] += tb[32 + (i & 3) + 8 * (i >> 2)]; }
;       }
;       if (MODE == 2) {
;         const float* tb = tbl + (kt - qr + 7) * 31 + (15 - qc);
; #pragma unroll
;         for (int i = 0; i < 16; ++i) {
;           const int kc0 = 4 * h + (i & 3) + 8 * (i >> 2), kc1 = kc0 + 32;
;           const bool v0 = (kc0 >= cs) && (kc0 < cs + 16), v1 = (kc1 >= cs) && (kc1 < cs + 16);
;           const float b0 = tb[v0 ? kc0 : qc], b1 = tb[v1 ? kc1 : qc];
;           s0[i] = v0 ? s0[i] + b0 : NEGBIG;
;           s1[i] = v1 ? s1[i] + b1 : NEGBIG;
;         }
;       }
;       float ma = __builtin_fmaxf(__builtin_fmaxf(s0[0], s0[1]), s0[2]), mb = __builtin_fmaxf(__builtin_fmaxf(s1[0], s1[1]), s1[2]);
; #pragma unroll
;       for (int i = 3; i < 15; i += 2) { ma = __builtin_fmaxf(__builtin_fmaxf(ma, s0[i]), s0[i + 1]); mb = __builtin_fmaxf(__builtin_fmaxf(mb, s1[i]), s1[i + 1]); }
;       float mt = __builtin_fmaxf(__builtin_fmaxf(ma, s0[15]), s1[15]);
;       mt = hmax(__builtin_fmaxf(mt, mb));
;       const bool fresh = !started && (mt > -1e29f);
;       if (__any(fresh || (started && mt > 8.f))) {
;         float delta = 0.f, al = 1.f;
;         if (fresh) { delta = mt; started = true; }
;         else if (started) { delta = __builtin_fmaxf(mt, 0.f); al = fexp2(-delta); }
;         mref += delta;
;         lsum *= al;
; #pragma unroll
;         for (int i = 0; i < 16; ++i) { o0[i] *= al; o1[i] *= al; s0[i] -= delta; s1[i] -= delta; negm[i] = -mref; }
;       }
.LBB0_116:
	ds_read_b128 v[50:53], v192
	ds_read_b128 v[54:57], v192 offset:32
	s_waitcnt lgkmcnt(1)
	v_mfma_f32_32x32x16_bf16 v[66:81], v[50:53], v[98:101], v[34:49]
	ds_read_b128 v[50:53], v192 offset:6656
	ds_read_b128 v[58:61], v192 offset:6688
	s_waitcnt lgkmcnt(1)
	v_mfma_f32_32x32x16_bf16 v[82:97], v[50:53], v[98:101], v[34:49]
	v_mfma_f32_32x32x16_bf16 v[66:81], v[54:57], v[102:105], v[66:81]
	ds_read_b128 v[50:53], v192 offset:64
	ds_read_b128 v[54:57], v192 offset:96
	s_waitcnt lgkmcnt(2)
	v_mfma_f32_32x32x16_bf16 v[82:97], v[58:61], v[102:105], v[82:97]
	s_waitcnt lgkmcnt(1)
	v_mfma_f32_32x32x16_bf16 v[66:81], v[50:53], v[106:109], v[66:81]
	ds_read_b128 v[50:53], v192 offset:6720
	ds_read_b128 v[58:61], v192 offset:6752
	s_waitcnt lgkmcnt(1)
	v_mfma_f32_32x32x16_bf16 v[82:97], v[50:53], v[106:109], v[82:97]
	v_mfma_f32_32x32x16_bf16 v[66:81], v[54:57], v[110:113], v[66:81]
	ds_read_b128 v[50:53], v192 offset:128
	ds_read_b128 v[54:57], v192 offset:160
	s_waitcnt lgkmcnt(2)
	v_mfma_f32_32x32x16_bf16 v[82:97], v[58:61], v[110:113], v[82:97]
	s_waitcnt lgkmcnt(1)
	v_mfma_f32_32x32x16_bf16 v[66:81], v[50:53], v[126:129], v[66:81]
	ds_read_b128 v[50:53], v192 offset:6784
	ds_read_b64_tr_b16 v[174:175], v191 offset:26624
	ds_read_b64_tr_b16 v[176:177], v191 offset:27776
	ds_read_b64_tr_b16 v[172:173], v191 offset:27840
	ds_read_b64_tr_b16 v[170:171], v191 offset:26688
	ds_read_b128 v[58:61], v192 offset:6816
	ds_read_b64_tr_b16 v[166:167], v191 offset:28928
	ds_read_b64_tr_b16 v[168:169], v191 offset:30080
	ds_read_b64_tr_b16 v[164:165], v191 offset:30144
	ds_read_b64_tr_b16 v[162:163], v191 offset:28992
	ds_read_b64_tr_b16 v[158:159], v191 offset:31232
	ds_read_b64_tr_b16 v[160:161], v191 offset:32384
	ds_read_b64_tr_b16 v[156:157], v191 offset:32448
	ds_read_b64_tr_b16 v[154:155], v191 offset:31296
	ds_read_b64_tr_b16 v[146:147], v191 offset:33536
	ds_read_b64_tr_b16 v[148:149], v191 offset:34688
	ds_read_b64_tr_b16 v[152:153], v191 offset:34752
	ds_read_b64_tr_b16 v[150:151], v191 offset:33600
	s_waitcnt lgkmcnt(14)
	v_mfma_f32_32x32x16_bf16 v[82:97], v[50:53], v[126:129], v[82:97]
	v_mfma_f32_32x32x16_bf16 v[66:81], v[54:57], v[130:133], v[66:81]
	s_waitcnt lgkmcnt(12)
	v_mfma_f32_32x32x16_bf16 v[82:97], v[58:61], v[130:133], v[82:97]
	s_nop 9
	v_max_f32_e32 v0, v67, v67
	v_max_f32_e32 v50, v66, v66
	v_max_f32_e32 v0, v50, v0
	v_max3_f32 v0, v0, v68, v69
	v_max3_f32 v0, v0, v70, v71
	v_max3_f32 v0, v0, v72, v73
	v_max3_f32 v0, v0, v74, v75
	v_max3_f32 v50, v82, v83, v84
	v_max3_f32 v50, v50, v85, v86
	v_max3_f32 v50, v50, v87, v88
	v_max3_f32 v50, v50, v89, v90
	v_max3_f32 v50, v50, v91, v92
	v_max3_f32 v0, v0, v76, v77
	v_max3_f32 v50, v50, v93, v94
	v_max3_f32 v0, v0, v78, v79
	v_max3_f32 v50, v50, v95, v96
	v_max3_f32 v0, v0, v80, v81
	v_max3_f32 v0, v0, v97, v50
	v_mov_b32_e32 v50, v0
	s_nop 1
	v_permlane32_swap_b32_e32 v0, v50
	v_max_f32_e32 v50, v50, v50
	v_max_f32_e32 v0, v0, v0
	v_max_f32_e32 v0, v0, v50
	v_cmp_lt_f32_e32 vcc, v234, v0
	s_cbranch_vccz .LBB0_118
	v_and_b32_e32 v50, 1, v211
	v_cmp_eq_u32_e64 s[12:13], 1, v50
	v_cmp_nlt_f32_e64 s[10:11], s33, v0
	s_nop 0
	v_max_f32_e32 v34, v0, v0
	v_max_f32_e32 v34, 0, v34
	v_exp_f32_e64 v35, -v34
	v_cndmask_b32_e64 v0, v0, 0, s[10:11]
	v_cndmask_b32_e64 v0, v0, v34, s[12:13]
	v_add_f32_e32 v210, v210, v0
	s_or_b64 vcc, s[10:11], s[12:13]
	v_cndmask_b32_e64 v34, 1.0, v35, s[12:13]
	v_xor_b32_e32 v50, 0x80000000, v210
	v_cndmask_b32_e32 v211, 1, v211, vcc
	v_and_b32_e32 v235, 1, v211
	v_cmp_eq_u32_e32 vcc, 1, v235
	v_mov_b32_e32 v235, 0x41000000
	v_mov_b32_e32 v236, 0xefa18f08
	v_cndmask_b32_e32 v234, v236, v235, vcc
	v_mul_f32_e32 v212, v212, v34
	v_pk_add_f32 v[66:67], v[66:67], v[0:1] op_sel_hi:[1,0] neg_lo:[0,1] neg_hi:[0,1]
	v_pk_add_f32 v[82:83], v[82:83], v[0:1] op_sel_hi:[1,0] neg_lo:[0,1] neg_hi:[0,1]
	v_pk_add_f32 v[68:69], v[68:69], v[0:1] op_sel_hi:[1,0] neg_lo:[0,1] neg_hi:[0,1]
	v_pk_add_f32 v[84:85], v[84:85], v[0:1] op_sel_hi:[1,0] neg_lo:[0,1] neg_hi:[0,1]
	v_pk_add_f32 v[70:71], v[70:71], v[0:1] op_sel_hi:[1,0] neg_lo:[0,1] neg_hi:[0,1]
	v_pk_add_f32 v[86:87], v[86:87], v[0:1] op_sel_hi:[1,0] neg_lo:[0,1] neg_hi:[0,1]
	v_pk_add_f32 v[72:73], v[72:73], v[0:1] op_sel_hi:[1,0] neg_lo:[0,1] neg_hi:[0,1]
	v_pk_add_f32 v[88:89], v[88:89], v[0:1] op_sel_hi:[1,0] neg_lo:[0,1] neg_hi:[0,1]
	v_pk_add_f32 v[74:75], v[74:75], v[0:1] op_sel_hi:[1,0] neg_lo:[0,1] neg_hi:[0,1]
	v_pk_add_f32 v[90:91], v[90:91], v[0:1] op_sel_hi:[1,0] neg_lo:[0,1] neg_hi:[0,1]
	v_pk_add_f32 v[76:77], v[76:77], v[0:1] op_sel_hi:[1,0] neg_lo:[0,1] neg_hi:[0,1]
	v_pk_add_f32 v[92:93], v[92:93], v[0:1] op_sel_hi:[1,0] neg_lo:[0,1] neg_hi:[0,1]
	v_pk_add_f32 v[78:79], v[78:79], v[0:1] op_sel_hi:[1,0] neg_lo:[0,1] neg_hi:[0,1]
	v_pk_add_f32 v[94:95], v[94:95], v[0:1] op_sel_hi:[1,0] neg_lo:[0,1] neg_hi:[0,1]
	v_pk_mul_f32 v[32:33], v[32:33], v[34:35] op_sel_hi:[1,0]
	v_pk_mul_f32 v[30:31], v[30:31], v[34:35] op_sel_hi:[1,0]
	v_pk_mul_f32 v[28:29], v[28:29], v[34:35] op_sel_hi:[1,0]
	v_pk_mul_f32 v[26:27], v[26:27], v[34:35] op_sel_hi:[1,0]
	v_pk_mul_f32 v[24:25], v[24:25], v[34:35] op_sel_hi:[1,0]
	v_pk_mul_f32 v[22:23], v[22:23], v[34:35] op_sel_hi:[1,0]
	v_pk_mul_f32 v[20:21], v[20:21], v[34:35] op_sel_hi:[1,0]
	v_pk_mul_f32 v[18:19], v[18:19], v[34:35] op_sel_hi:[1,0]
	v_pk_mul_f32 v[16:17], v[16:17], v[34:35] op_sel_hi:[1,0]
	v_pk_mul_f32 v[14:15], v[14:15], v[34:35] op_sel_hi:[1,0]
	v_pk_mul_f32 v[12:13], v[12:13], v[34:35] op_sel_hi:[1,0]
	v_pk_mul_f32 v[10:11], v[10:11], v[34:35] op_sel_hi:[1,0]
	v_pk_mul_f32 v[8:9], v[8:9], v[34:35] op_sel_hi:[1,0]
	v_pk_mul_f32 v[6:7], v[6:7], v[34:35] op_sel_hi:[1,0]
	v_pk_mul_f32 v[4:5], v[4:5], v[34:35] op_sel_hi:[1,0]
	v_pk_mul_f32 v[2:3], v[2:3], v[34:35] op_sel_hi:[1,0]
	v_pk_add_f32 v[80:81], v[80:81], v[0:1] op_sel_hi:[1,0] neg_lo:[0,1] neg_hi:[0,1]
	v_pk_add_f32 v[96:97], v[96:97], v[0:1] op_sel_hi:[1,0] neg_lo:[0,1] neg_hi:[0,1]
	v_mov_b32_e32 v51, v50
	v_mov_b32_e32 v52, v50
	v_mov_b32_e32 v53, v50
	v_mov_b32_e32 v54, v50
	v_mov_b32_e32 v55, v50
	v_mov_b32_e32 v56, v50
	v_mov_b32_e32 v57, v50
	v_mov_b32_e32 v58, v50
	v_mov_b32_e32 v59, v50
	v_mov_b32_e32 v60, v50
	v_mov_b32_e32 v61, v50
	v_mov_b32_e32 v62, v50
	v_mov_b32_e32 v63, v50
	v_mov_b32_e32 v64, v50
	v_mov_b32_e32 v65, v50
	v_mov_b32_e32 v34, v50
	v_mov_b32_e32 v35, v50
	v_mov_b32_e32 v36, v50
	v_mov_b32_e32 v37, v50
	v_mov_b32_e32 v38, v50
	v_mov_b32_e32 v39, v50
	v_mov_b32_e32 v40, v50
	v_mov_b32_e32 v41, v50
	v_mov_b32_e32 v42, v50
	v_mov_b32_e32 v43, v50
	v_mov_b32_e32 v44, v50
	v_mov_b32_e32 v45, v50
	v_mov_b32_e32 v46, v50
	v_mov_b32_e32 v47, v50
	v_mov_b32_e32 v48, v50
	v_mov_b32_e32 v49, v50
	s_branch .LBB0_119
; DI unsigned pack2(float a, float b) { f32x2 v = {a, b}; bf16v2 r = __builtin_convertvector(v, bf16v2); return __builtin_bit_cast(unsigned, r); }
; DI f32x16 mfma(bf16x8 a, bf16x8 b, f32x16 c) { return __builtin_amdgcn_mfma_f32_32x32x16_bf16(a, b, c, 0, 0, 0); }
; DI float fexp2(float x) { return __builtin_amdgcn_exp2f(x); }
; template <int MODE>
; DI void attn_tile(const Params& p, int layer, int tile, char* smem) {
;     ...
;       float ps = 0.f;
; #pragma unroll
;       for (int i = 0; i < 16; ++i) { s0[i] = fexp2(s0[i]); s1[i] = fexp2(s1[i]); ps += s0[i] + s1[i]; }
;       lsum += ps;
; #pragma unroll
;       for (int c = 0; c < 2; ++c) {
; #pragma unroll
;         for (int s = 0; s < 2; ++s) {
;           u32x4 pw;
;           if (c == 0) pw = (u32x4){pack2(s0[8 * s], s0[8 * s + 1]), pack2(s0[8 * s + 2], s0[8 * s + 3]), pack2(s0[8 * s + 4], s0[8 * s + 5]), pack2(s0[8 * s + 6], s0[8 * s + 7])};
;           else pw = (u32x4){pack2(s1[8 * s], s1[8 * s + 1]), pack2(s1[8 * s + 2], s1[8 * s + 3]), pack2(s1[8 * s + 4], s1[8 * s + 5]), pack2(s1[8 * s + 6], s1[8 * s + 7])};
;           const bf16x8 pf = __builtin_bit_cast(bf16x8, pw);
;           o0 = mfma(vf[2 * (2 * c + s)], pf, o0);
;           o1 = mfma(vf[2 * (2 * c + s) + 1], pf, o1);
;         }
;       }
.LBB0_118:
.LBB0_119:
	v_exp_f32_e32 v217, v66
	v_exp_f32_e32 v225, v67
	v_exp_f32_e32 v215, v68
	v_exp_f32_e32 v230, v69
	v_exp_f32_e32 v213, v70
	v_exp_f32_e32 v216, v71
	v_exp_f32_e32 v231, v72
	v_exp_f32_e32 v220, v73
	v_cvt_pk_bf16_f32 v66, v217, v225
	v_cvt_pk_bf16_f32 v67, v215, v230
	v_cvt_pk_bf16_f32 v68, v213, v216
	v_cvt_pk_bf16_f32 v69, v231, v220
	v_exp_f32_e32 v224, v82
	v_exp_f32_e32 v229, v83
	v_mfma_f32_32x32x16_bf16 v[18:33], v[174:177], v[66:69], v[18:33]
	v_exp_f32_e32 v214, v86
	v_exp_f32_e32 v233, v88
	v_exp_f32_e32 v226, v89
	v_exp_f32_e32 v221, v74
	v_exp_f32_e32 v222, v75
	v_exp_f32_e32 v223, v76
	v_exp_f32_e32 v88, v77
	v_mfma_f32_32x32x16_bf16 v[2:17], v[170:173], v[66:69], v[2:17]
	v_exp_f32_e32 v89, v78
	v_exp_f32_e32 v86, v79
	v_exp_f32_e32 v82, v80
	v_exp_f32_e32 v83, v81
	v_cvt_pk_bf16_f32 v66, v221, v222
	v_cvt_pk_bf16_f32 v67, v223, v88
	v_cvt_pk_bf16_f32 v68, v89, v86
	v_cvt_pk_bf16_f32 v69, v82, v83
	v_exp_f32_e32 v218, v84
	v_exp_f32_e32 v232, v85
	s_waitcnt lgkmcnt(10)
	v_mfma_f32_32x32x16_bf16 v[18:33], v[166:169], v[66:69], v[18:33]
	v_exp_f32_e32 v219, v87
	v_exp_f32_e32 v227, v90
	v_exp_f32_e32 v228, v91
	v_exp_f32_e32 v92, v92
	v_exp_f32_e32 v90, v93
	v_exp_f32_e32 v91, v94
	v_exp_f32_e32 v87, v95
	s_waitcnt lgkmcnt(8)
	v_mfma_f32_32x32x16_bf16 v[2:17], v[162:165], v[66:69], v[2:17]
	v_cvt_pk_bf16_f32 v66, v224, v229
	v_cvt_pk_bf16_f32 v67, v218, v232
	v_cvt_pk_bf16_f32 v68, v214, v219
	v_cvt_pk_bf16_f32 v69, v233, v226
	v_exp_f32_e32 v84, v96
	v_exp_f32_e32 v85, v97
	s_waitcnt lgkmcnt(6)
	v_mfma_f32_32x32x16_bf16 v[18:33], v[158:161], v[66:69], v[18:33]
	s_waitcnt lgkmcnt(4)
	v_mfma_f32_32x32x16_bf16 v[2:17], v[154:157], v[66:69], v[2:17]
	v_cvt_pk_bf16_f32 v66, v227, v228
	v_cvt_pk_bf16_f32 v67, v92, v90
	v_cvt_pk_bf16_f32 v68, v91, v87
	v_cvt_pk_bf16_f32 v69, v84, v85
	s_waitcnt lgkmcnt(2)
	s_nop 0
	v_mfma_f32_32x32x16_bf16 v[18:33], v[146:149], v[66:69], v[18:33]
	s_waitcnt lgkmcnt(0)
	v_mfma_f32_32x32x16_bf16 v[2:17], v[150:153], v[66:69], v[2:17]
	s_and_saveexec_b64 s[0:1], s[6:7]
	s_cbranch_execz .LBB0_121
	s_waitcnt vmcnt(5)
	ds_write_b128 v187, v[122:125] offset:13312

; DI f32x16 mfma(bf16x8 a, bf16x8 b, f32x16 c) { return __builtin_amdgcn_mfma_f32_32x32x16_bf16(a, b, c, 0, 0, 0); }
; template <int MODE>
; DI void attn_tile(const Params& p, int layer, int tile, char* smem) {
;     ...
;       f32x16 s0 = negm, s1 = negm;
; #pragma unroll
;       for (int d0 = 0; d0 < NKQ; ++d0) {
;         bf16x8 k0 = *(const bf16x8*)(Kb + d0 * 16);
;         bf16x8 k1 = *(const bf16x8*)(Kb + 32 * KROW + d0 * 16);
;         s0 = mfma(k0, qf[d0], s0);
;         s1 = mfma(k1, qf[d0], s1);
;       }
;       if (MODE == 0) {
;         const float* tb = tbl + (kt * 64 + 4 * h - qpos + 1280);
; #pragma unroll
;         for (int i = 0; i < 16; ++i) { s0[i] += tb[(i & 3) + 8 * (i >> 2)]; s1[i] += tb[32 + (i & 3) + 8 * (i >> 2)]; }
;       }
;       if (MODE == 2) {
;         const float* tb = tbl + (kt - qr + 7) * 31 + (15 - qc);
; #pragma unroll
;         for (int i = 0; i < 16; ++i) {
;           const int kc0 = 4 * h + (i & 3) + 8 * (i >> 2), kc1 = kc0 + 32;
;           const bool v0 = (kc0 >= cs) && (kc0 < cs + 16), v1 = (kc1 >= cs) && (kc1 < cs + 16);
;           const float b0 = tb[v0 ? kc0 : qc], b1 = tb[v1 ? kc1 : qc];
;           s0[i] = v0 ? s0[i] + b0 : NEGBIG;
;           s1[i] = v1 ? s1[i] + b1 : NEGBIG;
;         }
;       }
;       float ma = __builtin_fmaxf(__builtin_fmaxf(s0[0], s0[1]), s0[2]), mb = __builtin_fmaxf(__builtin_fmaxf(s1[0], s1[1]), s1[2]);
; #pragma unroll
;       for (int i = 3; i < 15; i += 2) { ma = __builtin_fmaxf(__builtin_fmaxf(ma, s0[i]), s0[i + 1]); mb = __builtin_fmaxf(__builtin_fmaxf(mb, s1[i]), s1[i + 1]); }
;       float mt = __builtin_fmaxf(__builtin_fmaxf(ma, s0[15]), s1[15]);
;       mt = hmax(__builtin_fmaxf(mt, mb));
;       const bool fresh = !started && (mt > -1e29f);
;       if (__any(fresh || (started && mt > 8.f))) {
;     ...
;     lstore(rk0, rv0, 1);
;     gload(rk0, rv0, kt0 + j + 3);
;     __syncthreads();
;     if (j + 1 >= ntile) break;
;     compute(1, kt0 + j + 1);
;     lstore(rk1, rv1, 0);
;     gload(rk1, rv1, kt0 + j + 4);
.LBB0_123:
	s_or_b64 exec, exec, s[0:1]
	s_add_i32 s21, s21, 2
	s_min_u32 s0, s21, 60
	s_lshl_b32 s0, s0, 6
	s_addk_i32 s0, 0xc0
	s_mul_i32 s1, s0, 0x180
	v_add_u32_e32 v0, s1, v182
	v_lshl_add_u64 v[66:67], v[0:1], 1, s[14:15]
	v_add_u32_e32 v0, s1, v184
	s_waitcnt vmcnt(3)
	ds_write_b128 v190, v[114:117] offset:35840
	v_lshl_add_u64 v[68:69], v[0:1], 1, s[14:15]
	v_lshl_add_u32 v0, s0, 8, v186
	global_load_dwordx4 v[122:125], v[66:67], off
	global_load_dwordx4 v[118:121], v[68:69], off
	v_lshl_add_u64 v[66:67], v[0:1], 1, s[16:17]
	global_load_dwordx4 v[114:117], v[66:67], off
	s_waitcnt lgkmcnt(0)
	s_barrier
	ds_read_b128 v[94:97], v192 offset:13312
	ds_read_b128 v[146:149], v192 offset:13376
	s_waitcnt lgkmcnt(1)
	v_mfma_f32_32x32x16_bf16 v[66:81], v[94:97], v[98:101], v[34:49]
	ds_read_b128 v[94:97], v192 offset:19968
	v_add_f32_e32 v0, v224, v217
	v_add_f32_e32 v0, 0, v0
	v_add_f32_e32 v93, v229, v225
	v_add_f32_e32 v0, v93, v0
	v_add_f32_e32 v93, v218, v215
	v_add_f32_e32 v0, v93, v0
	s_waitcnt lgkmcnt(0)
	v_mfma_f32_32x32x16_bf16 v[50:65], v[94:97], v[98:101], v[34:49]
	ds_read_b128 v[94:97], v192 offset:13344
	v_add_f32_e32 v93, v232, v230
	v_add_f32_e32 v0, v93, v0
	v_add_f32_e32 v93, v214, v213
	v_add_f32_e32 v0, v93, v0
	v_add_f32_e32 v93, v219, v216
	v_add_f32_e32 v0, v93, v0
	s_waitcnt lgkmcnt(0)
	v_mfma_f32_32x32x16_bf16 v[66:81], v[94:97], v[102:105], v[66:81]
	ds_read_b128 v[94:97], v192 offset:20000
	v_add_f32_e32 v93, v233, v231
	v_add_f32_e32 v0, v93, v0
	v_add_f32_e32 v93, v226, v220
	v_add_f32_e32 v0, v93, v0
	v_add_f32_e32 v93, v227, v221
	v_add_f32_e32 v0, v93, v0
	s_waitcnt lgkmcnt(0)
	v_mfma_f32_32x32x16_bf16 v[50:65], v[94:97], v[102:105], v[50:65]
	ds_read_b128 v[94:97], v192 offset:20032
	ds_read_b128 v[150:153], v192 offset:13408
	v_add_f32_e32 v93, v228, v222
	v_add_f32_e32 v0, v93, v0
	v_add_f32_e32 v92, v92, v223
	v_add_f32_e32 v0, v92, v0
	v_add_f32_e32 v88, v90, v88
	v_add_f32_e32 v0, v88, v0
	v_mfma_f32_32x32x16_bf16 v[66:81], v[146:149], v[106:109], v[66:81]
	ds_read_b128 v[146:149], v192 offset:20064
	v_add_f32_e32 v88, v91, v89
	v_add_f32_e32 v0, v88, v0
	ds_read_b128 v[88:91], v192 offset:13440
	v_add_f32_e32 v86, v87, v86
	v_add_f32_e32 v0, v86, v0
	v_add_f32_e32 v82, v84, v82
	s_waitcnt lgkmcnt(3)
	v_mfma_f32_32x32x16_bf16 v[50:65], v[94:97], v[106:109], v[50:65]
	v_add_f32_e32 v0, v82, v0
	v_add_f32_e32 v86, v85, v83
	ds_read_b128 v[82:85], v192 offset:20096
	ds_read_b128 v[162:165], v192 offset:13472
	v_add_f32_e32 v0, v86, v0
	v_add_f32_e32 v0, v212, v0
	s_waitcnt lgkmcnt(4)
	v_mfma_f32_32x32x16_bf16 v[66:81], v[150:153], v[110:113], v[66:81]
	ds_read_b64_tr_b16 v[158:159], v191 offset:35840
	ds_read_b64_tr_b16 v[160:161], v191 offset:36992
	ds_read_b64_tr_b16 v[156:157], v191 offset:37056
	ds_read_b64_tr_b16 v[154:155], v191 offset:35904
	ds_read_b128 v[166:169], v192 offset:20128
	ds_read_b64_tr_b16 v[150:151], v191 offset:38144
	s_waitcnt lgkmcnt(9)
	v_mfma_f32_32x32x16_bf16 v[50:65], v[146:149], v[110:113], v[50:65]
	s_waitcnt lgkmcnt(8)
	v_mfma_f32_32x32x16_bf16 v[66:81], v[88:91], v[126:129], v[66:81]
	ds_read_b64_tr_b16 v[152:153], v191 offset:39296
	ds_read_b64_tr_b16 v[148:149], v191 offset:39360
	ds_read_b64_tr_b16 v[146:147], v191 offset:38208
	ds_read_b64_tr_b16 v[94:95], v191 offset:40448
	ds_read_b64_tr_b16 v[96:97], v191 offset:41600
	ds_read_b64_tr_b16 v[92:93], v191 offset:41664
	ds_read_b64_tr_b16 v[90:91], v191 offset:40512
	s_waitcnt lgkmcnt(14)
	v_mfma_f32_32x32x16_bf16 v[50:65], v[82:85], v[126:129], v[50:65]
	ds_read_b64_tr_b16 v[82:83], v191 offset:42752
	ds_read_b64_tr_b16 v[84:85], v191 offset:43904
	ds_read_b64_tr_b16 v[88:89], v191 offset:43968
	ds_read_b64_tr_b16 v[86:87], v191 offset:42816
	s_waitcnt lgkmcnt(14)
	v_mfma_f32_32x32x16_bf16 v[66:81], v[162:165], v[130:133], v[66:81]
	s_waitcnt lgkmcnt(12)
	v_mfma_f32_32x32x16_bf16 v[50:65], v[166:169], v[130:133], v[50:65]
	s_nop 9
	v_max_f32_e32 v162, v67, v67
	v_max_f32_e32 v163, v66, v66
	v_max_f32_e32 v162, v163, v162
	v_max3_f32 v162, v162, v68, v69
	v_max3_f32 v162, v162, v70, v71
	v_max3_f32 v162, v162, v72, v73
	v_max3_f32 v162, v162, v74, v75
	v_max3_f32 v163, v50, v51, v52
	v_max3_f32 v163, v163, v53, v54
	v_max3_f32 v163, v163, v55, v56
	v_max3_f32 v163, v163, v57, v58
	v_max3_f32 v163, v163, v59, v60
	v_max3_f32 v162, v162, v76, v77
	v_max3_f32 v163, v163, v61, v62
	v_max3_f32 v162, v162, v78, v79
	v_max3_f32 v163, v163, v63, v64
	v_max3_f32 v162, v162, v80, v81
	v_max3_f32 v162, v162, v65, v163
	v_mov_b32_e32 v163, v162
	s_nop 1
	v_permlane32_swap_b32_e32 v162, v163
	v_max_f32_e32 v163, v163, v163
	v_max_f32_e32 v162, v162, v162
	v_max_f32_e32 v162, v162, v163
	v_cmp_lt_f32_e32 vcc, v234, v162
	s_cbranch_vccz .LBB0_125
; DI float fexp2(float x) { return __builtin_amdgcn_exp2f(x); }
; template <int MODE>
; DI void attn_tile(const Params& p, int layer, int tile, char* smem) {
;     ...
;       const bool fresh = !started && (mt > -1e29f);
;       if (__any(fresh || (started && mt > 8.f))) {
;         float delta = 0.f, al = 1.f;
;         if (fresh) { delta = mt; started = true; }
;         else if (started) { delta = __builtin_fmaxf(mt, 0.f); al = fexp2(-delta); }
;         mref += delta;
;         lsum *= al;
; #pragma unroll
;         for (int i = 0; i < 16; ++i) { o0[i] *= al; o1[i] *= al; s0[i] -= delta; s1[i] -= delta; negm[i] = -mref; }
;       }
	v_and_b32_e32 v163, 1, v211
	v_cmp_eq_u32_e64 s[12:13], 1, v163
	v_cmp_nlt_f32_e64 s[10:11], s33, v162
	s_nop 0
	v_max_f32_e32 v34, v162, v162
	v_max_f32_e32 v34, 0, v34
	v_exp_f32_e64 v35, -v34
	v_cndmask_b32_e64 v36, v162, 0, s[10:11]
	v_cndmask_b32_e64 v36, v36, v34, s[12:13]
	v_add_f32_e32 v210, v210, v36
	s_or_b64 vcc, s[10:11], s[12:13]
	v_cndmask_b32_e64 v38, 1.0, v35, s[12:13]
	v_xor_b32_e32 v34, 0x80000000, v210
	v_cndmask_b32_e32 v211, 1, v211, vcc
	v_and_b32_e32 v235, 1, v211
	v_cmp_eq_u32_e32 vcc, 1, v235
	v_mov_b32_e32 v235, 0x41000000
	v_mov_b32_e32 v236, 0xefa18f08
	v_cndmask_b32_e32 v234, v236, v235, vcc
	v_mul_f32_e32 v0, v0, v38
	v_pk_add_f32 v[66:67], v[66:67], v[36:37] op_sel_hi:[1,0] neg_lo:[0,1] neg_hi:[0,1]
	v_pk_add_f32 v[50:51], v[50:51], v[36:37] op_sel_hi:[1,0] neg_lo:[0,1] neg_hi:[0,1]
	v_pk_add_f32 v[68:69], v[68:69], v[36:37] op_sel_hi:[1,0] neg_lo:[0,1] neg_hi:[0,1]
	v_pk_add_f32 v[52:53], v[52:53], v[36:37] op_sel_hi:[1,0] neg_lo:[0,1] neg_hi:[0,1]
	v_pk_add_f32 v[70:71], v[70:71], v[36:37] op_sel_hi:[1,0] neg_lo:[0,1] neg_hi:[0,1]
	v_pk_add_f32 v[54:55], v[54:55], v[36:37] op_sel_hi:[1,0] neg_lo:[0,1] neg_hi:[0,1]
	v_pk_add_f32 v[72:73], v[72:73], v[36:37] op_sel_hi:[1,0] neg_lo:[0,1] neg_hi:[0,1]
	v_pk_add_f32 v[56:57], v[56:57], v[36:37] op_sel_hi:[1,0] neg_lo:[0,1] neg_hi:[0,1]
	v_pk_add_f32 v[74:75], v[74:75], v[36:37] op_sel_hi:[1,0] neg_lo:[0,1] neg_hi:[0,1]
	v_pk_add_f32 v[58:59], v[58:59], v[36:37] op_sel_hi:[1,0] neg_lo:[0,1] neg_hi:[0,1]
	v_pk_add_f32 v[76:77], v[76:77], v[36:37] op_sel_hi:[1,0] neg_lo:[0,1] neg_hi:[0,1]
	v_pk_add_f32 v[60:61], v[60:61], v[36:37] op_sel_hi:[1,0] neg_lo:[0,1] neg_hi:[0,1]
	v_pk_add_f32 v[78:79], v[78:79], v[36:37] op_sel_hi:[1,0] neg_lo:[0,1] neg_hi:[0,1]
	v_pk_add_f32 v[62:63], v[62:63], v[36:37] op_sel_hi:[1,0] neg_lo:[0,1] neg_hi:[0,1]
	v_pk_mul_f32 v[32:33], v[32:33], v[38:39] op_sel_hi:[1,0]
	v_pk_mul_f32 v[30:31], v[30:31], v[38:39] op_sel_hi:[1,0]
	v_pk_mul_f32 v[28:29], v[28:29], v[38:39] op_sel_hi:[1,0]
	v_pk_mul_f32 v[26:27], v[26:27], v[38:39] op_sel_hi:[1,0]
	v_pk_mul_f32 v[24:25], v[24:25], v[38:39] op_sel_hi:[1,0]
	v_pk_mul_f32 v[22:23], v[22:23], v[38:39] op_sel_hi:[1,0]
	v_pk_mul_f32 v[20:21], v[20:21], v[38:39] op_sel_hi:[1,0]
	v_pk_mul_f32 v[18:19], v[18:19], v[38:39] op_sel_hi:[1,0]
	v_pk_mul_f32 v[16:17], v[16:17], v[38:39] op_sel_hi:[1,0]
	v_pk_mul_f32 v[14:15], v[14:15], v[38:39] op_sel_hi:[1,0]
	v_pk_mul_f32 v[12:13], v[12:13], v[38:39] op_sel_hi:[1,0]
	v_pk_mul_f32 v[10:11], v[10:11], v[38:39] op_sel_hi:[1,0]
	v_pk_mul_f32 v[8:9], v[8:9], v[38:39] op_sel_hi:[1,0]
	v_pk_mul_f32 v[6:7], v[6:7], v[38:39] op_sel_hi:[1,0]
	v_pk_mul_f32 v[4:5], v[4:5], v[38:39] op_sel_hi:[1,0]
	v_pk_mul_f32 v[2:3], v[2:3], v[38:39] op_sel_hi:[1,0]
	v_pk_add_f32 v[80:81], v[80:81], v[36:37] op_sel_hi:[1,0] neg_lo:[0,1] neg_hi:[0,1]
	v_pk_add_f32 v[64:65], v[64:65], v[36:37] op_sel_hi:[1,0] neg_lo:[0,1] neg_hi:[0,1]
	v_mov_b32_e32 v35, v34
	v_mov_b32_e32 v36, v34
	v_mov_b32_e32 v37, v34
	v_mov_b32_e32 v38, v34
	v_mov_b32_e32 v39, v34
	v_mov_b32_e32 v40, v34
	v_mov_b32_e32 v41, v34
	v_mov_b32_e32 v42, v34
	v_mov_b32_e32 v43, v34
	v_mov_b32_e32 v44, v34
	v_mov_b32_e32 v45, v34
	v_mov_b32_e32 v46, v34
	v_mov_b32_e32 v47, v34
	v_mov_b32_e32 v48, v34
	v_mov_b32_e32 v49, v34

; template <int MODE>
; DI void attn_tile(const Params& p, int layer, int tile, char* smem) {
;     ...
;   f32x16 o0, o1, negm;
; #pragma unroll
;   for (int i = 0; i < 16; ++i) { o0[i] = 0.f; o1[i] = 0.f; negm[i] = 0.f; }
;   float mref = 0.f, lsum = 0.f;
;   bool started = false;
;   int qr = 0, qc = 0, cs = 0, rs = 0;
;   if (MODE == 2) { qr = qpos >> 6; qc = qpos & 63; cs = qc - 8; cs = cs < 0 ? 0 : (cs > 48 ? 48 : cs); rs = qr - 4; rs = rs < 0 ? 0 : (rs > 56 ? 56 : rs); }
;   const int i16 = lane & 15, qq = i16 >> 2, pp4 = i16 & 3, g16 = (lane >> 4) & 1;
;     ...
;   const int ntile = kt1 - kt0;
;   gload(rk1, rv1, kt0);
;   gload(rk0, rv0, kt0 + 1);
;   lstore(rk1, rv1, 0);
;   gload(rk1, rv1, kt0 + 2);
;   __syncthreads();
.LBB0_174:
	s_or_b64 exec, exec, s[0:1]
	s_add_i32 s0, s18, -14
	v_mul_lo_u32 v11, v11, s39
	v_lshlrev_b32_e32 v150, 1, v8
	s_min_u32 s0, s0, s19
	v_lshl_add_u32 v155, v11, 1, v150
	s_mul_i32 s0, s0, 0x26800
	s_waitcnt vmcnt(2)
	ds_write_b128 v155, v[2:5] offset:26624
	v_add_u32_e32 v2, s0, v156
	v_mov_b32_e32 v3, v1
	v_lshl_add_u64 v[2:3], v[2:3], 1, s[12:13]
	global_load_dwordx4 v[110:113], v[2:3], off
	v_add_u32_e32 v2, s0, v154
	v_mov_b32_e32 v3, v1
	v_lshl_add_u64 v[2:3], v[2:3], 1, s[14:15]
	global_load_dwordx4 v[102:105], v[2:3], off
	s_sub_i32 s21, s8, s18
	s_cmpk_lt_i32 s21, 0xffdd
	s_waitcnt lgkmcnt(0)
	s_barrier
	s_cbranch_scc1 .LBB0_188
	v_bfe_u32 v3, v148, 2, 2
	v_and_b32_e32 v4, 16, v148
	v_lshl_or_b32 v3, v149, 2, v3
	v_and_b32_e32 v10, 24, v10
	v_mul_u32_u24_e32 v5, 0x48, v147
	v_lshl_or_b32 v4, v4, 1, v10
	v_mul_u32_u24_e32 v3, 0x48, v3
	v_lshlrev_b32_e32 v2, 3, v149
	v_lshl_add_u32 v157, v3, 1, v4
	v_lshlrev_b32_e32 v3, 1, v5
	v_lshl_add_u32 v176, v2, 1, v3
	v_lshlrev_b32_e32 v2, 3, v7
	v_sub_u32_e32 v2, v148, v2
	v_lshl_add_u32 v177, v2, 4, v9
	v_lshlrev_b32_e32 v2, 1, v11
	v_lshl_add_u32 v178, v8, 1, v2
	v_lshl_or_b32 v0, s18, 8, v0
	v_lshlrev_b32_e32 v2, 2, v6
	v_sub_u32_e32 v0, v0, v2
	v_mov_b32_e32 v14, v1
	v_mov_b32_e32 v15, v1
	v_add_u32_e32 v180, 0xb400, v0
	v_mov_b32_e32 v0, v1
	v_mov_b32_e32 v2, v1
	v_mov_b32_e32 v3, v1
	v_mov_b32_e32 v4, v1
	v_mov_b32_e32 v5, v1
	v_mov_b32_e32 v6, v1
	v_mov_b32_e32 v7, v1
	v_mov_b32_e32 v8, v1
	v_mov_b32_e32 v9, v1
	v_mov_b32_e32 v10, v1
	v_mov_b32_e32 v11, v1
	v_mov_b32_e32 v12, v1
	v_mov_b32_e32 v13, v1
	v_mov_b64_e32 v[32:33], v[14:15]
	v_mov_b32_e32 v181, 0
	v_mov_b64_e32 v[30:31], v[12:13]
	v_mov_b64_e32 v[28:29], v[10:11]
	v_mov_b64_e32 v[26:27], v[8:9]
	v_mov_b64_e32 v[24:25], v[6:7]
	v_mov_b64_e32 v[22:23], v[4:5]
	v_mov_b64_e32 v[20:21], v[2:3]
	v_mov_b64_e32 v[18:19], v[0:1]
	v_mov_b64_e32 v[16:17], v[14:15]
	s_add_i32 s20, s21, 35
	s_add_i32 s21, s21, 34
	v_mov_b32_e32 v182, 0
	v_mov_b32_e32 v234, 0xefa18f08
	s_mov_b32 s23, -2
	v_mov_b32_e32 v179, 0
	v_mov_b64_e32 v[14:15], v[12:13]
	v_mov_b64_e32 v[12:13], v[10:11]
	v_mov_b64_e32 v[10:11], v[8:9]
	v_mov_b64_e32 v[8:9], v[6:7]
	v_mov_b64_e32 v[6:7], v[4:5]
	v_mov_b64_e32 v[4:5], v[2:3]
	v_mov_b64_e32 v[2:3], v[0:1]
	v_mov_b32_e32 v34, 0
	v_mov_b32_e32 v35, v181
	v_mov_b32_e32 v36, v181
	v_mov_b32_e32 v37, v181
	v_mov_b32_e32 v38, v181
	v_mov_b32_e32 v39, v181
	v_mov_b32_e32 v40, v181
	v_mov_b32_e32 v41, v181
	v_mov_b32_e32 v42, v181
	v_mov_b32_e32 v43, v181
	v_mov_b32_e32 v44, v181
	v_mov_b32_e32 v45, v181
	v_mov_b32_e32 v46, v181
	v_mov_b32_e32 v47, v181
	v_mov_b32_e32 v48, v181
	v_mov_b32_e32 v49, v181
	s_branch .LBB0_177

; DI f32x16 mfma(bf16x8 a, bf16x8 b, f32x16 c) { return __builtin_amdgcn_mfma_f32_32x32x16_bf16(a, b, c, 0, 0, 0); }
; template <int MODE>
; DI void attn_tile(const Params& p, int layer, int tile, char* smem) {
;     ...
;       f32x16 s0 = negm, s1 = negm;
; #pragma unroll
;       for (int d0 = 0; d0 < NKQ; ++d0) {
;         bf16x8 k0 = *(const bf16x8*)(Kb + d0 * 16);
;         bf16x8 k1 = *(const bf16x8*)(Kb + 32 * KROW + d0 * 16);
;         s0 = mfma(k0, qf[d0], s0);
;         s1 = mfma(k1, qf[d0], s1);
;       }
;       if (MODE == 0) {
;         const float* tb = tbl + (kt * 64 + 4 * h - qpos + 1280);
; #pragma unroll
;         for (int i = 0; i < 16; ++i) { s0[i] += tb[(i & 3) + 8 * (i >> 2)]; s1[i] += tb[32 + (i & 3) + 8 * (i >> 2)]; }
;       }
;       if (MODE == 2) {
;         const float* tb = tbl + (kt - qr + 7) * 31 + (15 - qc);
; #pragma unroll
;         for (int i = 0; i < 16; ++i) {
;           const int kc0 = 4 * h + (i & 3) + 8 * (i >> 2), kc1 = kc0 + 32;
;           const bool v0 = (kc0 >= cs) && (kc0 < cs + 16), v1 = (kc1 >= cs) && (kc1 < cs + 16);
;           const float b0 = tb[v0 ? kc0 : qc], b1 = tb[v1 ? kc1 : qc];
;           s0[i] = v0 ? s0[i] + b0 : NEGBIG;
;           s1[i] = v1 ? s1[i] + b1 : NEGBIG;
;         }
;       }
;       float ma = __builtin_fmaxf(__builtin_fmaxf(s0[0], s0[1]), s0[2]), mb = __builtin_fmaxf(__builtin_fmaxf(s1[0], s1[1]), s1[2]);
; #pragma unroll
;       for (int i = 3; i < 15; i += 2) { ma = __builtin_fmaxf(__builtin_fmaxf(ma, s0[i]), s0[i + 1]); mb = __builtin_fmaxf(__builtin_fmaxf(mb, s1[i]), s1[i + 1]); }
;       float mt = __builtin_fmaxf(__builtin_fmaxf(ma, s0[15]), s1[15]);
;       mt = hmax(__builtin_fmaxf(mt, mb));
;       const bool fresh = !started && (mt > -1e29f);
;       if (__any(fresh || (started && mt > 8.f))) {
.LBB0_177:
	ds_read_b128 v[66:69], v176
	ds_read_b128 v[114:117], v176 offset:32
	ds_read_b128 v[118:121], v176 offset:4608
	ds_read_b128 v[122:125], v176 offset:4640
	s_waitcnt lgkmcnt(3)
	v_mfma_f32_32x32x16_bf16 v[50:65], v[66:69], v[82:85], v[34:49]
	s_waitcnt lgkmcnt(1)
	v_mfma_f32_32x32x16_bf16 v[66:81], v[118:121], v[82:85], v[34:49]
	v_mfma_f32_32x32x16_bf16 v[50:65], v[114:117], v[86:89], v[50:65]
	ds_read_b128 v[114:117], v176 offset:64
	ds_read_b128 v[118:121], v176 offset:4672
	ds_read_b128 v[158:161], v176 offset:96
	ds_read_b64_tr_b16 v[142:143], v157 offset:26624
	ds_read_b64_tr_b16 v[144:145], v157 offset:27776
	ds_read_b64_tr_b16 v[140:141], v157 offset:27840
	ds_read_b64_tr_b16 v[138:139], v157 offset:26688
	ds_read_b64_tr_b16 v[134:135], v157 offset:28928
	ds_read_b64_tr_b16 v[136:137], v157 offset:30080
	ds_read_b64_tr_b16 v[132:133], v157 offset:30144
	ds_read_b64_tr_b16 v[130:131], v157 offset:28992
	ds_read_b128 v[162:165], v176 offset:4704
	s_waitcnt lgkmcnt(12)
	v_mfma_f32_32x32x16_bf16 v[66:81], v[122:125], v[86:89], v[66:81]
	s_waitcnt lgkmcnt(11)
	v_mfma_f32_32x32x16_bf16 v[50:65], v[114:117], v[90:93], v[50:65]
	s_waitcnt lgkmcnt(10)
	v_mfma_f32_32x32x16_bf16 v[66:81], v[118:121], v[90:93], v[66:81]
	ds_read_b64_tr_b16 v[126:127], v157 offset:31232
	ds_read_b64_tr_b16 v[128:129], v157 offset:32384
	ds_read_b64_tr_b16 v[124:125], v157 offset:32448
	ds_read_b64_tr_b16 v[122:123], v157 offset:31296
	ds_read_b64_tr_b16 v[114:115], v157 offset:33536
	ds_read_b64_tr_b16 v[116:117], v157 offset:34688
	ds_read_b64_tr_b16 v[120:121], v157 offset:34752
	ds_read_b64_tr_b16 v[118:119], v157 offset:33600
	ds_read2_b32 v[166:167], v180 offset1:1
	ds_read2_b32 v[168:169], v180 offset0:2 offset1:3
	ds_read2_b32 v[170:171], v180 offset0:8 offset1:9
	ds_read2_b32 v[174:175], v180 offset0:10 offset1:11
	s_waitcnt lgkmcnt(14)
	v_mfma_f32_32x32x16_bf16 v[50:65], v[158:161], v[94:97], v[50:65]
	s_waitcnt lgkmcnt(12)
	v_mfma_f32_32x32x16_bf16 v[66:81], v[162:165], v[94:97], v[66:81]
	s_waitcnt lgkmcnt(3)
	s_nop 8
	v_add_f32_e64 v160, v50, v166
	v_add_f32_e64 v161, v51, v167
	ds_read2_b32 v[50:51], v180 offset0:32 offset1:33
	ds_read2_b32 v[166:167], v180 offset0:34 offset1:35
	ds_read2_b32 v[184:185], v180 offset0:40 offset1:41
	ds_read2_b32 v[186:187], v180 offset0:42 offset1:43
	s_waitcnt lgkmcnt(6)
	v_pk_add_f32 v[172:173], v[52:53], v[168:169]
	s_waitcnt lgkmcnt(4)
	v_pk_add_f32 v[164:165], v[56:57], v[174:175]
	v_max_f32_e32 v0, v160, v161
	v_max3_f32 v0, v0, v172, v173
	s_waitcnt lgkmcnt(3)
	v_pk_add_f32 v[158:159], v[66:67], v[50:51]
	s_waitcnt lgkmcnt(2)
	v_pk_add_f32 v[68:69], v[68:69], v[166:167]
	v_pk_add_f32 v[166:167], v[54:55], v[170:171]
	ds_read2_b32 v[50:51], v180 offset0:16 offset1:17
	ds_read2_b32 v[52:53], v180 offset0:48 offset1:49
	ds_read2_b32 v[54:55], v180 offset0:18 offset1:19
	ds_read2_b32 v[56:57], v180 offset0:24 offset1:25
	ds_read2_b32 v[170:171], v180 offset0:26 offset1:27
	s_waitcnt lgkmcnt(6)
	v_pk_add_f32 v[66:67], v[70:71], v[184:185]
	s_waitcnt lgkmcnt(4)
	v_pk_add_f32 v[162:163], v[58:59], v[50:51]
	ds_read2_b32 v[50:51], v180 offset0:50 offset1:51
	ds_read2_b32 v[58:59], v180 offset0:56 offset1:57
	ds_read2_b32 v[184:185], v180 offset0:58 offset1:59
	v_pk_add_f32 v[70:71], v[72:73], v[186:187]
	v_max3_f32 v0, v0, v166, v167
	s_waitcnt lgkmcnt(2)
	v_pk_add_f32 v[76:77], v[76:77], v[50:51]
	v_max3_f32 v50, v158, v159, v68
	v_max3_f32 v50, v50, v69, v66
	v_pk_add_f32 v[74:75], v[74:75], v[52:53]
	v_max3_f32 v50, v50, v67, v70
	v_max3_f32 v0, v0, v164, v165
	v_pk_add_f32 v[174:175], v[60:61], v[54:55]
	v_max3_f32 v50, v50, v71, v74
	v_max3_f32 v0, v0, v162, v163
	v_pk_add_f32 v[168:169], v[62:63], v[56:57]
	s_waitcnt lgkmcnt(1)
	v_pk_add_f32 v[72:73], v[78:79], v[58:59]
	v_max3_f32 v50, v50, v75, v76
	v_max3_f32 v0, v0, v174, v175
	v_pk_add_f32 v[170:171], v[64:65], v[170:171]
	s_waitcnt lgkmcnt(0)
	v_pk_add_f32 v[78:79], v[80:81], v[184:185]
	v_max3_f32 v50, v50, v77, v72
	v_max3_f32 v0, v0, v168, v169
	v_max3_f32 v50, v50, v73, v78
	v_max3_f32 v0, v0, v170, v171
	v_max3_f32 v0, v0, v79, v50
	v_mov_b32_e32 v50, v0
	s_nop 1
	v_permlane32_swap_b32_e32 v0, v50
	v_max_f32_e32 v50, v50, v50
	v_max_f32_e32 v0, v0, v0
	v_max_f32_e32 v0, v0, v50
	v_cmp_lt_f32_e32 vcc, v234, v0
	s_cbranch_vccz .LBB0_179
; DI unsigned pack2(float a, float b) { f32x2 v = {a, b}; bf16v2 r = __builtin_convertvector(v, bf16v2); return __builtin_bit_cast(unsigned, r); }
; DI f32x16 mfma(bf16x8 a, bf16x8 b, f32x16 c) { return __builtin_amdgcn_mfma_f32_32x32x16_bf16(a, b, c, 0, 0, 0); }
; DI float fexp2(float x) { return __builtin_amdgcn_exp2f(x); }
; template <int MODE>
; DI void attn_tile(const Params& p, int layer, int tile, char* smem) {
;     ...
;       const bool fresh = !started && (mt > -1e29f);
;       if (__any(fresh || (started && mt > 8.f))) {
;         float delta = 0.f, al = 1.f;
;         if (fresh) { delta = mt; started = true; }
;         else if (started) { delta = __builtin_fmaxf(mt, 0.f); al = fexp2(-delta); }
;         mref += delta;
;         lsum *= al;
; #pragma unroll
;         for (int i = 0; i < 16; ++i) { o0[i] *= al; o1[i] *= al; s0[i] -= delta; s1[i] -= delta; negm[i] = -mref; }
;       }
;       float ps = 0.f;
; #pragma unroll
;       for (int i = 0; i < 16; ++i) { s0[i] = fexp2(s0[i]); s1[i] = fexp2(s1[i]); ps += s0[i] + s1[i]; }
;       lsum += ps;
; #pragma unroll
;       for (int c = 0; c < 2; ++c) {
; #pragma unroll
;         for (int s = 0; s < 2; ++s) {
;           u32x4 pw;
;           if (c == 0) pw = (u32x4){pack2(s0[8 * s], s0[8 * s + 1]), pack2(s0[8 * s + 2], s0[8 * s + 3]), pack2(s0[8 * s + 4], s0[8 * s + 5]), pack2(s0[8 * s + 6], s0[8 * s + 7])};
;           else pw = (u32x4){pack2(s1[8 * s], s1[8 * s + 1]), pack2(s1[8 * s + 2], s1[8 * s + 3]), pack2(s1[8 * s + 4], s1[8 * s + 5]), pack2(s1[8 * s + 6], s1[8 * s + 7])};
;           const bf16x8 pf = __builtin_bit_cast(bf16x8, pw);
;           o0 = mfma(vf[2 * (2 * c + s)], pf, o0);
;           o1 = mfma(vf[2 * (2 * c + s) + 1], pf, o1);
;         }
;       }
	v_and_b32_e32 v50, 1, v182
	v_cmp_eq_u32_e64 s[10:11], 1, v50
	v_cmp_nlt_f32_e64 s[8:9], s33, v0
	s_nop 0
	v_max_f32_e32 v34, v0, v0
	v_max_f32_e32 v34, 0, v34
	v_exp_f32_e64 v35, -v34
	v_cndmask_b32_e64 v0, v0, 0, s[8:9]
	v_cndmask_b32_e64 v34, v0, v34, s[10:11]
	v_add_f32_e32 v181, v181, v34
	s_or_b64 vcc, s[8:9], s[10:11]
	v_cndmask_b32_e64 v0, 1.0, v35, s[10:11]
	v_xor_b32_e32 v50, 0x80000000, v181
	v_cndmask_b32_e32 v182, 1, v182, vcc
	v_and_b32_e32 v235, 1, v182
	v_cmp_eq_u32_e32 vcc, 1, v235
	v_mov_b32_e32 v235, 0x41000000
	v_mov_b32_e32 v236, 0xefa18f08
	v_cndmask_b32_e32 v234, v236, v235, vcc
	v_mul_f32_e32 v179, v179, v0
	v_pk_mul_f32 v[32:33], v[32:33], v[0:1] op_sel_hi:[1,0]
	v_pk_mul_f32 v[30:31], v[30:31], v[0:1] op_sel_hi:[1,0]
	v_pk_mul_f32 v[28:29], v[28:29], v[0:1] op_sel_hi:[1,0]
	v_pk_mul_f32 v[26:27], v[26:27], v[0:1] op_sel_hi:[1,0]
	v_pk_mul_f32 v[24:25], v[24:25], v[0:1] op_sel_hi:[1,0]
	v_pk_mul_f32 v[22:23], v[22:23], v[0:1] op_sel_hi:[1,0]
	v_pk_mul_f32 v[20:21], v[20:21], v[0:1] op_sel_hi:[1,0]
	v_pk_mul_f32 v[18:19], v[18:19], v[0:1] op_sel_hi:[1,0]
	v_pk_mul_f32 v[16:17], v[16:17], v[0:1] op_sel_hi:[1,0]
	v_pk_mul_f32 v[14:15], v[14:15], v[0:1] op_sel_hi:[1,0]
	v_pk_mul_f32 v[12:13], v[12:13], v[0:1] op_sel_hi:[1,0]
	v_pk_mul_f32 v[10:11], v[10:11], v[0:1] op_sel_hi:[1,0]
	v_pk_mul_f32 v[8:9], v[8:9], v[0:1] op_sel_hi:[1,0]
	v_pk_mul_f32 v[6:7], v[6:7], v[0:1] op_sel_hi:[1,0]
	v_pk_mul_f32 v[4:5], v[4:5], v[0:1] op_sel_hi:[1,0]
	v_pk_mul_f32 v[2:3], v[2:3], v[0:1] op_sel_hi:[1,0]
	v_sub_f32_e32 v160, v160, v34
	v_sub_f32_e32 v161, v161, v34
	v_sub_f32_e32 v172, v172, v34
	v_sub_f32_e32 v173, v173, v34
	v_sub_f32_e32 v166, v166, v34
	v_sub_f32_e32 v167, v167, v34
	v_sub_f32_e32 v164, v164, v34
	v_sub_f32_e32 v165, v165, v34
	v_sub_f32_e32 v162, v162, v34
	v_sub_f32_e32 v163, v163, v34
	v_sub_f32_e32 v174, v174, v34
	v_sub_f32_e32 v175, v175, v34
	v_sub_f32_e32 v168, v168, v34
	v_sub_f32_e32 v169, v169, v34
	v_sub_f32_e32 v170, v170, v34
	v_sub_f32_e32 v171, v171, v34
	v_sub_f32_e32 v158, v158, v34
	v_sub_f32_e32 v159, v159, v34
	v_sub_f32_e32 v68, v68, v34
	v_sub_f32_e32 v69, v69, v34
	v_sub_f32_e32 v66, v66, v34
	v_sub_f32_e32 v67, v67, v34
	v_sub_f32_e32 v70, v70, v34
	v_sub_f32_e32 v71, v71, v34
	v_sub_f32_e32 v74, v74, v34
	v_sub_f32_e32 v75, v75, v34
	v_sub_f32_e32 v76, v76, v34
	v_sub_f32_e32 v77, v77, v34
	v_sub_f32_e32 v72, v72, v34
	v_sub_f32_e32 v73, v73, v34
	v_sub_f32_e32 v78, v78, v34
	v_sub_f32_e32 v79, v79, v34
	v_mov_b32_e32 v51, v50
	v_mov_b32_e32 v52, v50
	v_mov_b32_e32 v53, v50
	v_mov_b32_e32 v54, v50
	v_mov_b32_e32 v55, v50
	v_mov_b32_e32 v56, v50
	v_mov_b32_e32 v57, v50
	v_mov_b32_e32 v58, v50
	v_mov_b32_e32 v59, v50
	v_mov_b32_e32 v60, v50
	v_mov_b32_e32 v61, v50
	v_mov_b32_e32 v62, v50
	v_mov_b32_e32 v63, v50
	v_mov_b32_e32 v64, v50
	v_mov_b32_e32 v65, v50
	v_mov_b32_e32 v34, v50
	v_mov_b32_e32 v35, v50
	v_mov_b32_e32 v36, v50
	v_mov_b32_e32 v37, v50
	v_mov_b32_e32 v38, v50
	v_mov_b32_e32 v39, v50
	v_mov_b32_e32 v40, v50
	v_mov_b32_e32 v41, v50
	v_mov_b32_e32 v42, v50
	v_mov_b32_e32 v43, v50
	v_mov_b32_e32 v44, v50
	v_mov_b32_e32 v45, v50
	v_mov_b32_e32 v46, v50
	v_mov_b32_e32 v47, v50
	v_mov_b32_e32 v48, v50
	v_mov_b32_e32 v49, v50
	s_branch .LBB0_180
.LBB0_179:
.LBB0_180:
	v_exp_f32_e32 v0, v160
	v_exp_f32_e32 v80, v161
	v_exp_f32_e32 v81, v172
	v_exp_f32_e32 v160, v173
	v_exp_f32_e32 v161, v166
	v_exp_f32_e32 v166, v167
	v_exp_f32_e32 v164, v164
	v_exp_f32_e32 v165, v165
	v_cvt_pk_bf16_f32 v184, v0, v80
	v_cvt_pk_bf16_f32 v185, v81, v160
	v_cvt_pk_bf16_f32 v186, v161, v166
	v_cvt_pk_bf16_f32 v187, v164, v165
	v_exp_f32_e32 v162, v162
	v_exp_f32_e32 v69, v69
	v_mfma_f32_32x32x16_bf16 v[18:33], v[142:145], v[184:187], v[18:33]
	v_exp_f32_e32 v145, v163
	v_exp_f32_e32 v144, v174
	v_exp_f32_e32 v143, v175
	v_exp_f32_e32 v142, v168
	v_cvt_pk_bf16_f32 v168, v162, v145
	v_exp_f32_e32 v73, v73
	v_mfma_f32_32x32x16_bf16 v[2:17], v[138:141], v[184:187], v[2:17]
	v_exp_f32_e32 v140, v169
	v_exp_f32_e32 v139, v170
	v_exp_f32_e32 v138, v171
	v_cvt_pk_bf16_f32 v169, v144, v143
	v_cvt_pk_bf16_f32 v170, v142, v140
	v_cvt_pk_bf16_f32 v171, v139, v138
	s_nop 1
	v_mfma_f32_32x32x16_bf16 v[18:33], v[134:137], v[168:171], v[18:33]
	v_exp_f32_e32 v136, v158
	v_exp_f32_e32 v135, v159
	v_exp_f32_e32 v134, v68
	v_exp_f32_e32 v68, v66
	v_exp_f32_e32 v66, v71
	v_exp_f32_e32 v71, v72
	v_exp_f32_e32 v72, v78
	v_mfma_f32_32x32x16_bf16 v[2:17], v[130:133], v[168:171], v[2:17]
	v_exp_f32_e32 v130, v67
	v_exp_f32_e32 v67, v70
	v_cvt_pk_bf16_f32 v168, v136, v135
	v_cvt_pk_bf16_f32 v169, v134, v69
	v_cvt_pk_bf16_f32 v170, v68, v130
	v_cvt_pk_bf16_f32 v171, v67, v66
	v_exp_f32_e32 v70, v79
	v_cvt_pk_bf16_f32 v78, v71, v73
	v_mfma_f32_32x32x16_bf16 v[18:33], v[126:129], v[168:171], v[18:33]
	v_exp_f32_e32 v127, v74
	v_exp_f32_e32 v126, v75
	v_exp_f32_e32 v75, v76
	v_exp_f32_e32 v74, v77
	v_cvt_pk_bf16_f32 v79, v72, v70
	v_cvt_pk_bf16_f32 v76, v127, v126
	v_cvt_pk_bf16_f32 v77, v75, v74
	v_mfma_f32_32x32x16_bf16 v[2:17], v[122:125], v[168:171], v[2:17]
	s_nop 0
	v_mfma_f32_32x32x16_bf16 v[18:33], v[114:117], v[76:79], v[18:33]
	v_mfma_f32_32x32x16_bf16 v[2:17], v[118:121], v[76:79], v[2:17]
	s_and_saveexec_b64 s[0:1], s[6:7]
	s_cbranch_execz .LBB0_182
	s_waitcnt vmcnt(1)
	ds_write_b128 v177, v[106:109] offset:9216
; DI f32x16 mfma(bf16x8 a, bf16x8 b, f32x16 c) { return __builtin_amdgcn_mfma_f32_32x32x16_bf16(a, b, c, 0, 0, 0); }
; template <int MODE>
; DI void attn_tile(const Params& p, int layer, int tile, char* smem) {
;     ...
;       f32x16 s0 = negm, s1 = negm;
; #pragma unroll
;       for (int d0 = 0; d0 < NKQ; ++d0) {
;         bf16x8 k0 = *(const bf16x8*)(Kb + d0 * 16);
;         bf16x8 k1 = *(const bf16x8*)(Kb + 32 * KROW + d0 * 16);
;         s0 = mfma(k0, qf[d0], s0);
;         s1 = mfma(k1, qf[d0], s1);
;       }
;       if (MODE == 0) {
;         const float* tb = tbl + (kt * 64 + 4 * h - qpos + 1280);
; #pragma unroll
;         for (int i = 0; i < 16; ++i) { s0[i] += tb[(i & 3) + 8 * (i >> 2)]; s1[i] += tb[32 + (i & 3) + 8 * (i >> 2)]; }
;       }
;       if (MODE == 2) {
;         const float* tb = tbl + (kt - qr + 7) * 31 + (15 - qc);
; #pragma unroll
;         for (int i = 0; i < 16; ++i) {
;           const int kc0 = 4 * h + (i & 3) + 8 * (i >> 2), kc1 = kc0 + 32;
;           const bool v0 = (kc0 >= cs) && (kc0 < cs + 16), v1 = (kc1 >= cs) && (kc1 < cs + 16);
;           const float b0 = tb[v0 ? kc0 : qc], b1 = tb[v1 ? kc1 : qc];
;           s0[i] = v0 ? s0[i] + b0 : NEGBIG;
;           s1[i] = v1 ? s1[i] + b1 : NEGBIG;
;         }
;       }
;       float ma = __builtin_fmaxf(__builtin_fmaxf(s0[0], s0[1]), s0[2]), mb = __builtin_fmaxf(__builtin_fmaxf(s1[0], s1[1]), s1[2]);
; #pragma unroll
;       for (int i = 3; i < 15; i += 2) { ma = __builtin_fmaxf(__builtin_fmaxf(ma, s0[i]), s0[i + 1]); mb = __builtin_fmaxf(__builtin_fmaxf(mb, s1[i]), s1[i + 1]); }
;       float mt = __builtin_fmaxf(__builtin_fmaxf(ma, s0[15]), s1[15]);
;       mt = hmax(__builtin_fmaxf(mt, mb));
;       const bool fresh = !started && (mt > -1e29f);
;       if (__any(fresh || (started && mt > 8.f))) {
;     ...
;     lstore(rk0, rv0, 1);
;     gload(rk0, rv0, kt0 + j + 3);
;     __syncthreads();
;     if (j + 1 >= ntile) break;
;     compute(1, kt0 + j + 1);
;     lstore(rk1, rv1, 0);
;     gload(rk1, rv1, kt0 + j + 4);
.LBB0_182:
	s_or_b64 exec, exec, s[0:1]
	v_add_f32_e32 v0, v136, v0
	v_add_f32_e32 v0, 0, v0
	v_add_f32_e32 v76, v135, v80
	v_add_f32_e32 v0, v76, v0
	v_add_f32_e32 v76, v134, v81
	v_add_f32_e32 v0, v76, v0
	v_add_f32_e32 v69, v69, v160
	v_add_f32_e32 v0, v69, v0
	v_add_f32_e32 v68, v68, v161
	v_add_f32_e32 v0, v68, v0
	v_add_f32_e32 v68, v130, v166
	v_add_f32_e32 v0, v68, v0
	v_add_f32_e32 v67, v67, v164
	v_add_f32_e32 v0, v67, v0
	v_add_f32_e32 v66, v66, v165
	v_add_f32_e32 v0, v66, v0
	v_add_f32_e32 v66, v127, v162
	v_add_f32_e32 v0, v66, v0
	v_add_f32_e32 v66, v126, v145
	v_add_f32_e32 v0, v66, v0
	v_add_f32_e32 v66, v75, v144
	v_add_f32_e32 v0, v66, v0
	v_add_f32_e32 v66, v74, v143
	v_add_f32_e32 v0, v66, v0
	v_add_f32_e32 v66, v71, v142
	v_add_f32_e32 v0, v66, v0
	v_add_f32_e32 v66, v73, v140
	s_add_i32 s22, s23, 2
	s_add_i32 s23, s18, s23
	v_add_f32_e32 v0, v66, v0
	v_add_f32_e32 v66, v72, v139
	s_add_i32 s0, s23, -11
	v_add_f32_e32 v0, v66, v0
	v_add_f32_e32 v66, v70, v138
	s_min_i32 s0, s0, s19
	v_add_f32_e32 v0, v66, v0
	s_mul_i32 s0, s0, 0x26800
	v_add_f32_e32 v179, v179, v0
	v_add_u32_e32 v0, s0, v156
	v_lshl_add_u64 v[66:67], v[0:1], 1, s[12:13]
	v_add_u32_e32 v0, s0, v154
	global_load_dwordx4 v[106:109], v[66:67], off
	v_lshl_add_u64 v[66:67], v[0:1], 1, s[14:15]
	s_waitcnt vmcnt(1)
	ds_write_b128 v178, v[98:101] offset:35840
	global_load_dwordx4 v[98:101], v[66:67], off
	s_mov_b64 s[0:1], -1
	s_cmp_ge_i32 s22, s20
	s_waitcnt lgkmcnt(0)
	s_barrier
	s_cbranch_scc1 .LBB0_187
	ds_read_b128 v[114:117], v176 offset:9216
	ds_read_b128 v[118:121], v176 offset:9248
	s_waitcnt lgkmcnt(1)
	v_mfma_f32_32x32x16_bf16 v[66:81], v[114:117], v[82:85], v[34:49]
	ds_read_b128 v[114:117], v176 offset:13824
	ds_read_b128 v[122:125], v176 offset:13856
	s_waitcnt lgkmcnt(1)
	v_mfma_f32_32x32x16_bf16 v[50:65], v[114:117], v[82:85], v[34:49]
	v_mfma_f32_32x32x16_bf16 v[66:81], v[118:121], v[86:89], v[66:81]
	ds_read_b128 v[114:117], v176 offset:9280
	ds_read_b128 v[118:121], v176 offset:13888
	ds_read_b128 v[158:161], v176 offset:9312
	ds_read_b64_tr_b16 v[142:143], v157 offset:35840
	ds_read_b64_tr_b16 v[144:145], v157 offset:36992
	ds_read_b64_tr_b16 v[140:141], v157 offset:37056
	ds_read_b64_tr_b16 v[138:139], v157 offset:35904
	ds_read_b64_tr_b16 v[134:135], v157 offset:38144
	ds_read_b64_tr_b16 v[136:137], v157 offset:39296
	ds_read_b64_tr_b16 v[132:133], v157 offset:39360
	ds_read_b64_tr_b16 v[130:131], v157 offset:38208
	ds_read_b128 v[162:165], v176 offset:13920
	s_waitcnt lgkmcnt(12)
	v_mfma_f32_32x32x16_bf16 v[50:65], v[122:125], v[86:89], v[50:65]
	s_waitcnt lgkmcnt(11)
	v_mfma_f32_32x32x16_bf16 v[66:81], v[114:117], v[90:93], v[66:81]
	s_waitcnt lgkmcnt(10)
	v_mfma_f32_32x32x16_bf16 v[50:65], v[118:121], v[90:93], v[50:65]
	ds_read_b64_tr_b16 v[126:127], v157 offset:40448
	ds_read_b64_tr_b16 v[128:129], v157 offset:41600
	ds_read_b64_tr_b16 v[124:125], v157 offset:41664
	ds_read_b64_tr_b16 v[122:123], v157 offset:40512
	ds_read_b64_tr_b16 v[114:115], v157 offset:42752
	ds_read_b64_tr_b16 v[116:117], v157 offset:43904
	ds_read_b64_tr_b16 v[120:121], v157 offset:43968
	ds_read_b64_tr_b16 v[118:119], v157 offset:42816
	ds_read2_b32 v[166:167], v180 offset0:64 offset1:65
	s_waitcnt lgkmcnt(14)
	v_mfma_f32_32x32x16_bf16 v[66:81], v[158:161], v[94:97], v[66:81]
	ds_read2_b32 v[160:161], v180 offset0:66 offset1:67
	ds_read2_b32 v[168:169], v180 offset0:72 offset1:73
	ds_read2_b32 v[170:171], v180 offset0:74 offset1:75
	s_waitcnt lgkmcnt(12)
	v_mfma_f32_32x32x16_bf16 v[50:65], v[162:165], v[94:97], v[50:65]
	s_waitcnt lgkmcnt(3)
	s_nop 5
	v_add_f32_e64 v158, v66, v166
	v_add_f32_e64 v159, v67, v167
	ds_read2_b32 v[66:67], v180 offset0:96 offset1:97
	ds_read2_b32 v[166:167], v180 offset0:98 offset1:99
	ds_read2_b32 v[172:173], v180 offset0:104 offset1:105
	ds_read2_b32 v[174:175], v180 offset0:106 offset1:107
	s_waitcnt lgkmcnt(6)
	v_pk_add_f32 v[162:163], v[68:69], v[160:161]
	s_waitcnt lgkmcnt(5)
	v_pk_add_f32 v[160:161], v[70:71], v[168:169]
	s_waitcnt lgkmcnt(4)
	v_pk_add_f32 v[70:71], v[72:73], v[170:171]
	v_max_f32_e32 v0, v158, v159
	v_max3_f32 v0, v0, v162, v163
	s_waitcnt lgkmcnt(3)
	v_pk_add_f32 v[66:67], v[50:51], v[66:67]
	s_waitcnt lgkmcnt(2)
	v_pk_add_f32 v[52:53], v[52:53], v[166:167]
	s_waitcnt lgkmcnt(1)
	v_pk_add_f32 v[50:51], v[54:55], v[172:173]
	s_waitcnt lgkmcnt(0)
	v_pk_add_f32 v[54:55], v[56:57], v[174:175]
	ds_read2_b32 v[56:57], v180 offset0:80 offset1:81
	ds_read2_b32 v[72:73], v180 offset0:112 offset1:113
	ds_read2_b32 v[164:165], v180 offset0:82 offset1:83
	ds_read2_b32 v[166:167], v180 offset0:88 offset1:89
	ds_read2_b32 v[168:169], v180 offset0:90 offset1:91
	s_waitcnt lgkmcnt(4)
	v_pk_add_f32 v[68:69], v[74:75], v[56:57]
	ds_read2_b32 v[56:57], v180 offset0:114 offset1:115
	ds_read2_b32 v[74:75], v180 offset0:120 offset1:121
	ds_read2_b32 v[170:171], v180 offset0:122 offset1:123
	v_max3_f32 v0, v0, v160, v161
	s_waitcnt lgkmcnt(6)
	v_pk_add_f32 v[58:59], v[58:59], v[72:73]
	s_waitcnt lgkmcnt(2)
	v_pk_add_f32 v[60:61], v[60:61], v[56:57]
	s_waitcnt lgkmcnt(1)
	v_pk_add_f32 v[56:57], v[62:63], v[74:75]
	s_waitcnt lgkmcnt(0)
	v_pk_add_f32 v[62:63], v[64:65], v[170:171]
	v_max3_f32 v64, v66, v67, v52
	v_max3_f32 v64, v64, v53, v50
	v_max3_f32 v64, v64, v51, v54
	v_max3_f32 v0, v0, v70, v71
	v_pk_add_f32 v[76:77], v[76:77], v[164:165]
	v_max3_f32 v64, v64, v55, v58
	v_max3_f32 v0, v0, v68, v69
	v_pk_add_f32 v[72:73], v[78:79], v[166:167]
	v_max3_f32 v64, v64, v59, v60
	v_max3_f32 v0, v0, v76, v77
	v_pk_add_f32 v[74:75], v[80:81], v[168:169]
	v_max3_f32 v64, v64, v61, v56
	v_max3_f32 v0, v0, v72, v73
	v_max3_f32 v64, v64, v57, v62
	v_max3_f32 v0, v0, v74, v75
	v_max3_f32 v0, v0, v63, v64
	v_mov_b32_e32 v64, v0
	s_nop 1
	v_permlane32_swap_b32_e32 v0, v64
	v_max_f32_e32 v64, v64, v64
	v_max_f32_e32 v0, v0, v0
	v_max_f32_e32 v0, v0, v64
	v_cmp_lt_f32_e32 vcc, v234, v0
	s_cbranch_vccz .LBB0_185
; DI float fexp2(float x) { return __builtin_amdgcn_exp2f(x); }
; template <int MODE>
; DI void attn_tile(const Params& p, int layer, int tile, char* smem) {
;     ...
;       const bool fresh = !started && (mt > -1e29f);
;       if (__any(fresh || (started && mt > 8.f))) {
;         float delta = 0.f, al = 1.f;
;         if (fresh) { delta = mt; started = true; }
;         else if (started) { delta = __builtin_fmaxf(mt, 0.f); al = fexp2(-delta); }
;         mref += delta;
;         lsum *= al;
; #pragma unroll
;         for (int i = 0; i < 16; ++i) { o0[i] *= al; o1[i] *= al; s0[i] -= delta; s1[i] -= delta; negm[i] = -mref; }
;       }
	v_and_b32_e32 v64, 1, v182
	v_cmp_eq_u32_e64 s[10:11], 1, v64
	v_cmp_nlt_f32_e64 s[8:9], s33, v0
	s_nop 0
	v_max_f32_e32 v34, v0, v0
	v_max_f32_e32 v34, 0, v34
	v_exp_f32_e64 v35, -v34
	v_cndmask_b32_e64 v0, v0, 0, s[8:9]
	v_cndmask_b32_e64 v36, v0, v34, s[10:11]
	v_add_f32_e32 v181, v181, v36
	s_or_b64 vcc, s[8:9], s[10:11]
	v_cndmask_b32_e64 v0, 1.0, v35, s[10:11]
	v_xor_b32_e32 v34, 0x80000000, v181
	v_cndmask_b32_e32 v182, 1, v182, vcc
	v_and_b32_e32 v235, 1, v182
	v_cmp_eq_u32_e32 vcc, 1, v235
	v_mov_b32_e32 v235, 0x41000000
	v_mov_b32_e32 v236, 0xefa18f08
	v_cndmask_b32_e32 v234, v236, v235, vcc
	v_mul_f32_e32 v179, v179, v0
	v_pk_mul_f32 v[32:33], v[32:33], v[0:1] op_sel_hi:[1,0]
	v_pk_mul_f32 v[30:31], v[30:31], v[0:1] op_sel_hi:[1,0]
	v_pk_mul_f32 v[28:29], v[28:29], v[0:1] op_sel_hi:[1,0]
	v_pk_mul_f32 v[26:27], v[26:27], v[0:1] op_sel_hi:[1,0]
	v_pk_mul_f32 v[24:25], v[24:25], v[0:1] op_sel_hi:[1,0]
	v_pk_mul_f32 v[22:23], v[22:23], v[0:1] op_sel_hi:[1,0]
	v_pk_mul_f32 v[20:21], v[20:21], v[0:1] op_sel_hi:[1,0]
	v_pk_mul_f32 v[18:19], v[18:19], v[0:1] op_sel_hi:[1,0]
	v_pk_mul_f32 v[16:17], v[16:17], v[0:1] op_sel_hi:[1,0]
	v_pk_mul_f32 v[14:15], v[14:15], v[0:1] op_sel_hi:[1,0]
	v_pk_mul_f32 v[12:13], v[12:13], v[0:1] op_sel_hi:[1,0]
	v_pk_mul_f32 v[10:11], v[10:11], v[0:1] op_sel_hi:[1,0]
	v_pk_mul_f32 v[8:9], v[8:9], v[0:1] op_sel_hi:[1,0]
	v_pk_mul_f32 v[6:7], v[6:7], v[0:1] op_sel_hi:[1,0]
	v_pk_mul_f32 v[4:5], v[4:5], v[0:1] op_sel_hi:[1,0]
	v_pk_mul_f32 v[2:3], v[2:3], v[0:1] op_sel_hi:[1,0]
	v_sub_f32_e32 v158, v158, v36
	v_sub_f32_e32 v159, v159, v36
	v_sub_f32_e32 v162, v162, v36
	v_sub_f32_e32 v163, v163, v36
	v_sub_f32_e32 v160, v160, v36
	v_sub_f32_e32 v161, v161, v36
	v_sub_f32_e32 v70, v70, v36
	v_sub_f32_e32 v71, v71, v36
	v_sub_f32_e32 v68, v68, v36
	v_sub_f32_e32 v69, v69, v36
	v_sub_f32_e32 v76, v76, v36
	v_sub_f32_e32 v77, v77, v36
	v_sub_f32_e32 v72, v72, v36
	v_sub_f32_e32 v73, v73, v36
	v_sub_f32_e32 v74, v74, v36
	v_sub_f32_e32 v75, v75, v36
	v_sub_f32_e32 v66, v66, v36
	v_sub_f32_e32 v67, v67, v36
	v_sub_f32_e32 v52, v52, v36
	v_sub_f32_e32 v53, v53, v36
	v_sub_f32_e32 v50, v50, v36
	v_sub_f32_e32 v51, v51, v36
	v_sub_f32_e32 v54, v54, v36
	v_sub_f32_e32 v55, v55, v36
	v_sub_f32_e32 v58, v58, v36
	v_sub_f32_e32 v59, v59, v36
	v_sub_f32_e32 v60, v60, v36
	v_sub_f32_e32 v61, v61, v36
	v_sub_f32_e32 v56, v56, v36
	v_sub_f32_e32 v57, v57, v36
	v_sub_f32_e32 v62, v62, v36
	v_sub_f32_e32 v63, v63, v36
	v_mov_b32_e32 v35, v34
	v_mov_b32_e32 v36, v34
	v_mov_b32_e32 v37, v34
	v_mov_b32_e32 v38, v34
	v_mov_b32_e32 v39, v34
	v_mov_b32_e32 v40, v34
	v_mov_b32_e32 v41, v34
	v_mov_b32_e32 v42, v34
	v_mov_b32_e32 v43, v34
	v_mov_b32_e32 v44, v34
	v_mov_b32_e32 v45, v34
	v_mov_b32_e32 v46, v34
	v_mov_b32_e32 v47, v34
	v_mov_b32_e32 v48, v34
	v_mov_b32_e32 v49, v34

; template <int MODE>
; DI void attn_tile(const Params& p, int layer, int tile, char* smem) {
;     ...
;   if (MODE == 2) { qr = qpos >> 6; qc = qpos & 63; cs = qc - 8; cs = cs < 0 ? 0 : (cs > 48 ? 48 : cs); rs = qr - 4; rs = rs < 0 ? 0 : (rs > 56 ? 56 : rs); }
;     ...
;       if (MODE == 2) {
;         const float* tb = tbl + (kt - qr + 7) * 31 + (15 - qc);
; #pragma unroll
;         for (int i = 0; i < 16; ++i) {
;           const int kc0 = 4 * h + (i & 3) + 8 * (i >> 2), kc1 = kc0 + 32;
;           const bool v0 = (kc0 >= cs) && (kc0 < cs + 16), v1 = (kc1 >= cs) && (kc1 < cs + 16);
;           const float b0 = tb[v0 ? kc0 : qc], b1 = tb[v1 ? kc1 : qc];
;           s0[i] = v0 ? s0[i] + b0 : NEGBIG;
;           s1[i] = v1 ? s1[i] + b1 : NEGBIG;
;         }
.LBB0_209:
	s_or_b64 exec, exec, s[0:1]
	s_movk_i32 s0, 0x48
	v_mul_lo_u32 v11, v11, s0
	s_or_b32 s0, s81, 2
	s_min_i32 s0, s0, s86
	v_lshlrev_b32_e32 v154, 1, v6
	s_mul_i32 s0, s0, 0x26800
	v_lshl_add_u32 v157, v11, 1, v154
	v_add_u32_e32 v0, s0, v158
	s_waitcnt vmcnt(2)
	ds_write_b128 v157, v[2:5] offset:26624
	v_lshl_add_u64 v[2:3], v[0:1], 1, s[92:93]
	v_add_u32_e32 v0, s0, v156
	global_load_dwordx4 v[120:123], v[2:3], off
	v_lshl_add_u64 v[2:3], v[0:1], 1, s[4:5]
	global_load_dwordx4 v[124:127], v[2:3], off
	s_sub_i32 s83, s8, s81
	s_add_i32 s83, s83, 7
	s_cmp_lt_i32 s83, 1
	s_waitcnt lgkmcnt(0)
	s_barrier
	s_cbranch_scc1 .LBB0_227
	v_ashrrev_i32_e32 v2, 6, v150
	v_and_b32_e32 v3, 63, v8
	v_med3_i32 v8, v2, 4, 60
	v_add_u32_e32 v159, -4, v8
	v_add_u32_e32 v160, 4, v8
	v_mul_u32_u24_e32 v8, 0x48, v149
	v_lshlrev_b32_e32 v0, 3, v151
	v_med3_u32 v4, v3, 8, 56
	v_lshlrev_b32_e32 v14, 2, v151
	v_lshlrev_b32_e32 v8, 1, v8
	v_add_u32_e32 v5, -8, v4
	v_lshl_add_u32 v162, v0, 1, v8
	v_add_u32_e32 v0, 8, v4
	v_or_b32_e32 v4, 32, v14
	v_or_b32_e32 v8, 16, v14
	v_cmp_ge_u32_e32 vcc, v4, v5
	v_cmp_lt_u32_e64 s[10:11], v8, v5
	v_or_b32_e32 v15, 33, v14
	v_or_b32_e32 v16, 17, v14
	s_and_b64 s[10:11], vcc, s[10:11]
	v_cmp_ge_u32_e32 vcc, v15, v5
	v_cmp_lt_u32_e64 s[14:15], v16, v5
	v_or_b32_e32 v19, 34, v14
	v_or_b32_e32 v20, 18, v14
	s_and_b64 s[14:15], vcc, s[14:15]
	v_cmp_ge_u32_e32 vcc, v19, v5
	v_cmp_lt_u32_e64 s[18:19], v20, v5
	v_or_b32_e32 v23, 35, v14
	v_or_b32_e32 v24, 19, v14
	s_and_b64 s[18:19], vcc, s[18:19]
	v_cmp_ge_u32_e32 vcc, v23, v5
	v_cmp_lt_u32_e64 s[22:23], v24, v5
	v_or_b32_e32 v27, 40, v14
	v_or_b32_e32 v28, 24, v14
	s_and_b64 s[22:23], vcc, s[22:23]
	v_cmp_ge_u32_e32 vcc, v27, v5
	v_cmp_lt_u32_e64 s[26:27], v28, v5
	v_or_b32_e32 v31, 41, v14
	v_or_b32_e32 v32, 25, v14
	s_and_b64 s[26:27], vcc, s[26:27]
	v_cmp_ge_u32_e32 vcc, v31, v5
	v_cmp_lt_u32_e64 s[30:31], v32, v5
	v_or_b32_e32 v35, 42, v14
	v_or_b32_e32 v36, 26, v14
	s_and_b64 s[30:31], vcc, s[30:31]
	v_cmp_ge_u32_e32 vcc, v35, v5
	v_cmp_lt_u32_e64 s[36:37], v36, v5
	v_or_b32_e32 v39, 43, v14
	v_or_b32_e32 v40, 27, v14
	s_and_b64 s[36:37], vcc, s[36:37]
	v_cmp_ge_u32_e32 vcc, v39, v5
	v_cmp_lt_u32_e64 s[40:41], v40, v5
	v_lshrrev_b32_e32 v12, 2, v148
	v_cmp_lt_u32_e64 s[8:9], v14, v5
	s_and_b64 s[40:41], vcc, s[40:41]
	v_cmp_ge_u32_e32 vcc, v8, v5
	v_and_b32_e32 v13, 16, v148
	v_and_or_b32 v12, v12, 3, v14
	v_and_b32_e32 v10, 24, v10
	s_and_b64 s[42:43], vcc, s[8:9]
	v_cmp_ge_u32_e32 vcc, v16, v5
	v_cmp_lt_u32_e64 s[46:47], v16, v0
	v_lshl_or_b32 v10, v13, 1, v10
	v_mul_u32_u24_e32 v12, 0x48, v12
	v_or_b32_e32 v42, 48, v14
	v_cmp_lt_u32_e64 s[44:45], v4, v5
	s_and_b64 s[46:47], vcc, s[46:47]
	v_cmp_ge_u32_e32 vcc, v20, v5
	v_cmp_lt_u32_e64 s[50:51], v20, v0
	v_lshl_add_u32 v161, v12, 1, v10
	v_cndmask_b32_e64 v12, v3, v4, s[10:11]
	v_cndmask_b32_e64 v4, v3, v42, s[44:45]
	v_or_b32_e32 v42, 49, v14
	v_cmp_lt_u32_e64 s[48:49], v15, v5
	s_and_b64 s[50:51], vcc, s[50:51]
	v_cmp_ge_u32_e32 vcc, v24, v5
	v_cmp_lt_u32_e64 s[54:55], v24, v0
	v_cndmask_b32_e64 v17, v3, v15, s[14:15]
	v_cndmask_b32_e64 v15, v3, v42, s[48:49]
	v_or_b32_e32 v42, 50, v14
	v_cmp_lt_u32_e64 s[52:53], v19, v5
	s_and_b64 s[54:55], vcc, s[54:55]
	v_cmp_ge_u32_e32 vcc, v28, v5
	v_cmp_lt_u32_e64 s[58:59], v28, v0
	v_cndmask_b32_e64 v21, v3, v19, s[18:19]
	v_cndmask_b32_e64 v19, v3, v42, s[52:53]
	v_or_b32_e32 v42, 51, v14
	v_cmp_lt_u32_e64 s[56:57], v23, v5
	s_and_b64 s[58:59], vcc, s[58:59]
	v_cmp_ge_u32_e32 vcc, v32, v5
	v_cmp_lt_u32_e64 s[62:63], v32, v0
	v_cndmask_b32_e64 v25, v3, v23, s[22:23]
	v_cndmask_b32_e64 v23, v3, v42, s[56:57]
	v_or_b32_e32 v42, 56, v14
	v_cmp_lt_u32_e64 s[60:61], v27, v5
	s_and_b64 s[62:63], vcc, s[62:63]
	v_cmp_ge_u32_e32 vcc, v36, v5
	v_cmp_lt_u32_e64 s[66:67], v36, v0
	v_writelane_b32 v255, s35, 57
	v_or_b32_e32 v13, 1, v14
	v_or_b32_e32 v18, 2, v14
	v_or_b32_e32 v22, 3, v14
	v_or_b32_e32 v26, 8, v14
	v_cndmask_b32_e64 v29, v3, v27, s[26:27]
	v_or_b32_e32 v30, 9, v14
	v_or_b32_e32 v34, 10, v14
	v_or_b32_e32 v38, 11, v14
	v_cndmask_b32_e64 v27, v3, v42, s[60:61]
; template <int MODE>
; DI void attn_tile(const Params& p, int layer, int tile, char* smem) {
;     ...
;   f32x16 o0, o1, negm;
; #pragma unroll
;   for (int i = 0; i < 16; ++i) { o0[i] = 0.f; o1[i] = 0.f; negm[i] = 0.f; }
;   float mref = 0.f, lsum = 0.f;
;     ...
;       if (MODE == 2) {
;         const float* tb = tbl + (kt - qr + 7) * 31 + (15 - qc);
; #pragma unroll
;         for (int i = 0; i < 16; ++i) {
;           const int kc0 = 4 * h + (i & 3) + 8 * (i >> 2), kc1 = kc0 + 32;
;           const bool v0 = (kc0 >= cs) && (kc0 < cs + 16), v1 = (kc1 >= cs) && (kc1 < cs + 16);
;           const float b0 = tb[v0 ? kc0 : qc], b1 = tb[v1 ? kc1 : qc];
;           s0[i] = v0 ? s0[i] + b0 : NEGBIG;
;           s1[i] = v1 ? s1[i] + b1 : NEGBIG;
;         }
	v_or_b32_e32 v42, 57, v14
	v_cmp_lt_u32_e64 s[64:65], v31, v5
	s_and_b64 s[66:67], vcc, s[66:67]
	v_cmp_ge_u32_e32 vcc, v40, v5
	v_cmp_lt_u32_e64 s[70:71], v40, v0
	v_writelane_b32 v255, s29, 58
	v_cndmask_b32_e64 v10, v14, v3, s[8:9]
	v_cmp_lt_u32_e64 s[12:13], v13, v5
	v_cmp_lt_u32_e64 s[16:17], v18, v5
	v_cmp_lt_u32_e64 s[20:21], v22, v5
	v_cmp_lt_u32_e64 s[24:25], v26, v5
	v_cmp_lt_u32_e64 s[28:29], v30, v5
	v_cndmask_b32_e64 v33, v3, v31, s[30:31]
	v_cmp_lt_u32_e64 s[34:35], v34, v5
	v_cmp_lt_u32_e64 s[38:39], v38, v5
	v_cndmask_b32_e64 v31, v3, v42, s[64:65]
	v_or_b32_e32 v42, 58, v14
	v_cmp_lt_u32_e64 s[68:69], v35, v5
	v_or_b32_e32 v14, 59, v14
	s_and_b64 s[70:71], vcc, s[70:71]
	v_cmp_lt_u32_e64 s[72:73], v39, v5
	v_cndmask_b32_e64 v13, v13, v3, s[12:13]
	v_cndmask_b32_e64 v18, v18, v3, s[16:17]
	v_cndmask_b32_e64 v22, v22, v3, s[20:21]
	v_cndmask_b32_e64 v26, v26, v3, s[24:25]
	v_cndmask_b32_e64 v30, v30, v3, s[28:29]
	v_cndmask_b32_e64 v34, v34, v3, s[34:35]
	v_cndmask_b32_e64 v37, v3, v35, s[36:37]
	v_cndmask_b32_e64 v38, v38, v3, s[38:39]
	v_cndmask_b32_e64 v41, v3, v39, s[40:41]
	v_cndmask_b32_e64 v8, v3, v8, s[42:43]
	v_cndmask_b32_e64 v16, v3, v16, s[46:47]
	v_cndmask_b32_e64 v20, v3, v20, s[50:51]
	v_cndmask_b32_e64 v24, v3, v24, s[54:55]
	v_cndmask_b32_e64 v28, v3, v28, s[58:59]
	v_cndmask_b32_e64 v32, v3, v32, s[62:63]
	v_cndmask_b32_e64 v36, v3, v36, s[66:67]
	v_cndmask_b32_e64 v35, v3, v42, s[68:69]
	v_cndmask_b32_e64 v0, v3, v40, s[70:71]
	v_cndmask_b32_e64 v5, v3, v14, s[72:73]
	v_lshlrev_b32_e32 v7, 3, v7
	s_mul_i32 s0, s81, 0x7c
	v_lshlrev_b32_e32 v3, 2, v3
	v_sub_u32_e32 v7, v148, v7
	v_sub_u32_e32 v3, s0, v3
	s_movk_i32 s0, 0x7c
	v_lshl_add_u32 v163, v7, 4, v9
	v_lshlrev_b32_e32 v7, 1, v11
	v_mul_lo_u32 v2, v2, s0
	v_lshlrev_b32_e32 v186, 2, v15
	v_mov_b32_e32 v14, v1
	v_mov_b32_e32 v15, v1
	v_lshl_add_u32 v164, v6, 1, v7
	v_lshlrev_b32_e32 v165, 2, v10
	v_sub_u32_e32 v177, v3, v2
	v_lshlrev_b32_e32 v166, 2, v12
	v_lshlrev_b32_e32 v167, 2, v13
	v_lshlrev_b32_e32 v168, 2, v17
	v_lshlrev_b32_e32 v169, 2, v18
	v_lshlrev_b32_e32 v170, 2, v21
	v_lshlrev_b32_e32 v171, 2, v22
	v_lshlrev_b32_e32 v172, 2, v25
	v_lshlrev_b32_e32 v173, 2, v26
	v_lshlrev_b32_e32 v175, 2, v29
	v_lshlrev_b32_e32 v176, 2, v30
	v_lshlrev_b32_e32 v178, 2, v33
	v_lshlrev_b32_e32 v179, 2, v34
	v_lshlrev_b32_e32 v180, 2, v37
	v_lshlrev_b32_e32 v181, 2, v38
	v_lshlrev_b32_e32 v182, 2, v41
	v_lshlrev_b32_e32 v183, 2, v8
	v_lshlrev_b32_e32 v184, 2, v4
	v_lshlrev_b32_e32 v185, 2, v16
	v_lshlrev_b32_e32 v187, 2, v20
	v_lshlrev_b32_e32 v188, 2, v19
	v_lshlrev_b32_e32 v189, 2, v24
	v_lshlrev_b32_e32 v190, 2, v23
	v_lshlrev_b32_e32 v191, 2, v28
	v_lshlrev_b32_e32 v192, 2, v27
	v_lshlrev_b32_e32 v193, 2, v32
	v_lshlrev_b32_e32 v210, 2, v31
	v_lshlrev_b32_e32 v211, 2, v36
	v_lshlrev_b32_e32 v212, 2, v35
	v_lshlrev_b32_e32 v213, 2, v0
	v_lshlrev_b32_e32 v214, 2, v5
	v_mov_b32_e32 v0, v1
	v_mov_b32_e32 v2, v1
	v_mov_b32_e32 v3, v1
	v_mov_b32_e32 v4, v1
	v_mov_b32_e32 v5, v1
	v_mov_b32_e32 v6, v1
	v_mov_b32_e32 v7, v1
	v_mov_b32_e32 v8, v1
	v_mov_b32_e32 v9, v1
	v_mov_b32_e32 v10, v1
	v_mov_b32_e32 v11, v1
	v_mov_b32_e32 v12, v1
	v_mov_b32_e32 v13, v1
	v_mov_b64_e32 v[62:63], v[14:15]
	v_mov_b64_e32 v[30:31], v[14:15]
	v_mov_b64_e32 v[46:47], v[14:15]
	s_mov_b32 s87, 0
	v_mov_b32_e32 v215, 0
	v_mov_b32_e32 v216, 0
	v_mov_b32_e32 v234, 0xefa18f08
	v_mov_b64_e32 v[60:61], v[12:13]
	v_mov_b64_e32 v[58:59], v[10:11]
	v_mov_b64_e32 v[56:57], v[8:9]
	v_mov_b64_e32 v[54:55], v[6:7]
	v_mov_b64_e32 v[52:53], v[4:5]
	v_mov_b64_e32 v[50:51], v[2:3]
	v_mov_b64_e32 v[48:49], v[0:1]
	v_mov_b64_e32 v[28:29], v[12:13]
	v_mov_b64_e32 v[26:27], v[10:11]
	v_mov_b64_e32 v[24:25], v[8:9]
	v_mov_b64_e32 v[22:23], v[6:7]
	v_mov_b64_e32 v[20:21], v[4:5]
	v_mov_b64_e32 v[18:19], v[2:3]
	v_mov_b64_e32 v[16:17], v[0:1]
	v_mov_b64_e32 v[44:45], v[12:13]
	v_mov_b64_e32 v[42:43], v[10:11]
	v_mov_b64_e32 v[40:41], v[8:9]
	v_mov_b64_e32 v[38:39], v[6:7]
	v_mov_b64_e32 v[36:37], v[4:5]
	v_mov_b64_e32 v[34:35], v[2:3]
	v_mov_b64_e32 v[32:33], v[0:1]
	v_mov_b32_e32 v174, 0
	s_branch .LBB0_212

; DI f32x16 mfma(bf16x8 a, bf16x8 b, f32x16 c) { return __builtin_amdgcn_mfma_f32_32x32x16_bf16(a, b, c, 0, 0, 0); }
; template <int MODE>
; DI void attn_tile(const Params& p, int layer, int tile, char* smem) {
;     ...
;     if (MODE == 2) active = (kt >= rs) && (kt < rs + 8);
;     if (active) {
;       const u16* Kb = Ks + buf * 64 * KROW + r * KROW + 8 * h;
;       const u16* Vb = Vs + buf * 64 * VROW;
;       bf16x8 vf[8];
; #pragma unroll
;       for (int cs2 = 0; cs2 < 4; ++cs2) {
;         const u16* vp = Vb + (16 * cs2 + 4 * h + qq) * VROW + 16 * g16 + 4 * pp4;
;         { s16x4 lo = tr_read(vp), hi = tr_read(vp + 8 * VROW); vf[2 * cs2] = __builtin_shufflevector(lo, hi, 0, 1, 2, 3, 4, 5, 6, 7); }
;         { s16x4 lo = tr_read(vp + 32), hi = tr_read(vp + 8 * VROW + 32); vf[2 * cs2 + 1] = __builtin_shufflevector(lo, hi, 0, 1, 2, 3, 4, 5, 6, 7); }
;       }
;       f32x16 s0 = negm, s1 = negm;
; #pragma unroll
;       for (int d0 = 0; d0 < NKQ; ++d0) {
;         bf16x8 k0 = *(const bf16x8*)(Kb + d0 * 16);
;         bf16x8 k1 = *(const bf16x8*)(Kb + 32 * KROW + d0 * 16);
;         s0 = mfma(k0, qf[d0], s0);
;         s1 = mfma(k1, qf[d0], s1);
;       }
;       if (MODE == 0) {
;         const float* tb = tbl + (kt * 64 + 4 * h - qpos + 1280);
; #pragma unroll
;         for (int i = 0; i < 16; ++i) { s0[i] += tb[(i & 3) + 8 * (i >> 2)]; s1[i] += tb[32 + (i & 3) + 8 * (i >> 2)]; }
;       }
;       if (MODE == 2) {
;         const float* tb = tbl + (kt - qr + 7) * 31 + (15 - qc);
; #pragma unroll
;         for (int i = 0; i < 16; ++i) {
;           const int kc0 = 4 * h + (i & 3) + 8 * (i >> 2), kc1 = kc0 + 32;
;           const bool v0 = (kc0 >= cs) && (kc0 < cs + 16), v1 = (kc1 >= cs) && (kc1 < cs + 16);
;           const float b0 = tb[v0 ? kc0 : qc], b1 = tb[v1 ? kc1 : qc];
;           s0[i] = v0 ? s0[i] + b0 : NEGBIG;
;           s1[i] = v1 ? s1[i] + b1 : NEGBIG;
;         }
.LBB0_212:
	s_add_i32 s82, s81, s87
	v_cmp_ge_i32_e32 vcc, s82, v159
	v_cmp_lt_i32_e64 s[74:75], s82, v160
	s_and_b64 s[74:75], vcc, s[74:75]
	s_and_saveexec_b64 s[0:1], s[74:75]
	s_cbranch_execz .LBB0_216
	ds_read_b128 v[2:5], v162
	ds_read_b128 v[6:9], v162 offset:32
	v_add_u32_e32 v0, v177, v165
	v_add_u32_e32 v14, v177, v166
	v_add_u32_e32 v15, v177, v167
	s_waitcnt lgkmcnt(1)
	v_mfma_f32_32x32x16_bf16 v[64:79], v[2:5], v[96:99], v[48:63]
	ds_read_b128 v[2:5], v162 offset:4608
	ds_read_b128 v[10:13], v162 offset:4640
	ds_read_b128 v[132:135], v162 offset:64
	v_add_u32_e32 v204, v177, v168
	v_add_u32_e32 v205, v177, v169
	v_add_u32_e32 v208, v177, v170
	v_add_u32_e32 v209, v177, v171
	v_add_u32_e32 v217, v177, v172
	s_waitcnt lgkmcnt(2)
	v_mfma_f32_32x32x16_bf16 v[80:95], v[2:5], v[96:99], v[48:63]
	s_waitcnt lgkmcnt(1)
	v_mfma_f32_32x32x16_bf16 v[80:95], v[10:13], v[100:103], v[80:95]
	v_mfma_f32_32x32x16_bf16 v[64:79], v[6:9], v[100:103], v[64:79]
	ds_read_b64_tr_b16 v[128:129], v161 offset:26624
	ds_read_b64_tr_b16 v[130:131], v161 offset:27776
	ds_read_b64_tr_b16 v[12:13], v161 offset:27840
	ds_read_b64_tr_b16 v[10:11], v161 offset:26688
	ds_read_b64_tr_b16 v[6:7], v161 offset:28928
	ds_read_b64_tr_b16 v[8:9], v161 offset:30080
	ds_read_b64_tr_b16 v[4:5], v161 offset:30144
	ds_read_b64_tr_b16 v[2:3], v161 offset:28992
	ds_read_b128 v[218:221], v162 offset:4672
	ds_read_b128 v[222:225], v162 offset:96
	s_waitcnt lgkmcnt(1)
	v_mfma_f32_32x32x16_bf16 v[80:95], v[218:221], v[104:107], v[80:95]
	v_mfma_f32_32x32x16_bf16 v[64:79], v[132:135], v[104:107], v[64:79]
	ds_read_b64_tr_b16 v[144:145], v161 offset:31232
	ds_read_b64_tr_b16 v[146:147], v161 offset:32384
	ds_read_b64_tr_b16 v[142:143], v161 offset:32448
	ds_read_b64_tr_b16 v[140:141], v161 offset:31296
	ds_read_b64_tr_b16 v[136:137], v161 offset:33536
	ds_read_b64_tr_b16 v[138:139], v161 offset:34688
	ds_read_b64_tr_b16 v[134:135], v161 offset:34752
	ds_read_b64_tr_b16 v[132:133], v161 offset:33600
	ds_read_b128 v[226:229], v162 offset:4704
	ds_read_b32 v0, v0 offset:45984
	ds_read_b32 v14, v14 offset:45984
	ds_read_b32 v15, v15 offset:45984
	ds_read_b32 v204, v204 offset:45984
	ds_read_b32 v205, v205 offset:45984
	ds_read_b32 v208, v208 offset:45984
	ds_read_b32 v209, v209 offset:45984
	ds_read_b32 v217, v217 offset:45984
	s_waitcnt lgkmcnt(8)
	v_mfma_f32_32x32x16_bf16 v[80:95], v[226:229], v[108:111], v[80:95]
	v_mfma_f32_32x32x16_bf16 v[64:79], v[222:225], v[108:111], v[64:79]
	s_waitcnt lgkmcnt(6)
	s_nop 9
	v_add_f32_e32 v14, v80, v14
	v_add_f32_e32 v0, v64, v0
	v_cndmask_b32_e64 v64, v206, v14, s[10:11]
	s_waitcnt lgkmcnt(5)
	v_add_f32_e32 v14, v65, v15
	v_cndmask_b32_e64 v65, v14, v206, s[12:13]
	s_waitcnt lgkmcnt(4)
	v_add_f32_e32 v14, v81, v204
	v_cndmask_b32_e64 v80, v206, v14, s[14:15]
	s_waitcnt lgkmcnt(3)
	v_add_f32_e32 v14, v66, v205
	s_waitcnt lgkmcnt(2)
	v_add_f32_e32 v15, v82, v208
	s_waitcnt lgkmcnt(1)
	v_add_f32_e32 v66, v67, v209
	s_waitcnt lgkmcnt(0)
	v_add_f32_e32 v67, v83, v217
	v_add_u32_e32 v81, v177, v173
	v_add_u32_e32 v82, v177, v175
	v_add_u32_e32 v83, v177, v176
	v_add_u32_e32 v204, v177, v178
	v_add_u32_e32 v205, v177, v179
	v_add_u32_e32 v208, v177, v180
	v_add_u32_e32 v209, v177, v181
	v_add_u32_e32 v217, v177, v182
	ds_read_b32 v81, v81 offset:45984
	ds_read_b32 v82, v82 offset:45984
	ds_read_b32 v83, v83 offset:45984
	ds_read_b32 v204, v204 offset:45984
	ds_read_b32 v205, v205 offset:45984
	ds_read_b32 v208, v208 offset:45984
	ds_read_b32 v209, v209 offset:45984
	ds_read_b32 v217, v217 offset:45984
	s_waitcnt lgkmcnt(7)
	v_add_f32_e32 v68, v68, v81
	v_cndmask_b32_e64 v81, v68, v206, s[24:25]
	s_waitcnt lgkmcnt(6)
	v_add_f32_e32 v68, v84, v82
	v_cndmask_b32_e64 v82, v206, v68, s[26:27]
	s_waitcnt lgkmcnt(5)
	v_add_f32_e32 v68, v69, v83
	v_cndmask_b32_e64 v83, v68, v206, s[28:29]
	s_waitcnt lgkmcnt(4)
	v_add_f32_e32 v68, v85, v204
	v_cndmask_b32_e64 v84, v206, v68, s[30:31]
	s_waitcnt lgkmcnt(3)
	v_add_f32_e32 v68, v70, v205
	s_waitcnt lgkmcnt(2)
	v_add_f32_e32 v69, v86, v208
	s_waitcnt lgkmcnt(1)
	v_add_f32_e32 v70, v71, v209
	s_waitcnt lgkmcnt(0)
	v_add_f32_e32 v71, v87, v217
	v_add_u32_e32 v85, v177, v183
	v_add_u32_e32 v86, v177, v184
	v_add_u32_e32 v87, v177, v185
	v_add_u32_e32 v204, v177, v186
	v_add_u32_e32 v205, v177, v187
	v_add_u32_e32 v208, v177, v188
	v_add_u32_e32 v209, v177, v189
	v_add_u32_e32 v217, v177, v190
	ds_read_b32 v85, v85 offset:45984
	ds_read_b32 v86, v86 offset:45984
	ds_read_b32 v87, v87 offset:45984
	ds_read_b32 v204, v204 offset:45984
	ds_read_b32 v205, v205 offset:45984
	ds_read_b32 v208, v208 offset:45984
	ds_read_b32 v209, v209 offset:45984
	ds_read_b32 v217, v217 offset:45984
	s_waitcnt lgkmcnt(7)
	v_add_f32_e32 v72, v72, v85
	v_cndmask_b32_e64 v85, v206, v72, s[42:43]
	s_waitcnt lgkmcnt(6)
	v_add_f32_e32 v72, v88, v86
	v_cndmask_b32_e64 v86, v206, v72, s[44:45]
	s_waitcnt lgkmcnt(5)
	v_add_f32_e32 v72, v73, v87
	v_cndmask_b32_e64 v87, v206, v72, s[46:47]
	s_waitcnt lgkmcnt(4)
	v_add_f32_e32 v72, v89, v204
	v_cndmask_b32_e64 v88, v206, v72, s[48:49]
	s_waitcnt lgkmcnt(3)
	v_add_f32_e32 v72, v74, v205
	s_waitcnt lgkmcnt(2)
	v_add_f32_e32 v73, v90, v208
	s_waitcnt lgkmcnt(1)
	v_add_f32_e32 v74, v75, v209
	s_waitcnt lgkmcnt(0)
; DI float fexp2(float x) { return __builtin_amdgcn_exp2f(x); }
; template <int MODE>
; DI void attn_tile(const Params& p, int layer, int tile, char* smem) {
;     ...
;       float ma = __builtin_fmaxf(__builtin_fmaxf(s0[0], s0[1]), s0[2]), mb = __builtin_fmaxf(__builtin_fmaxf(s1[0], s1[1]), s1[2]);
; #pragma unroll
;       for (int i = 3; i < 15; i += 2) { ma = __builtin_fmaxf(__builtin_fmaxf(ma, s0[i]), s0[i + 1]); mb = __builtin_fmaxf(__builtin_fmaxf(mb, s1[i]), s1[i + 1]); }
;       float mt = __builtin_fmaxf(__builtin_fmaxf(ma, s0[15]), s1[15]);
;       mt = hmax(__builtin_fmaxf(mt, mb));
;       const bool fresh = !started && (mt > -1e29f);
;       if (__any(fresh || (started && mt > 8.f))) {
;         float delta = 0.f, al = 1.f;
;         if (fresh) { delta = mt; started = true; }
;         else if (started) { delta = __builtin_fmaxf(mt, 0.f); al = fexp2(-delta); }
;         mref += delta;
;         lsum *= al;
; #pragma unroll
;         for (int i = 0; i < 16; ++i) { o0[i] *= al; o1[i] *= al; s0[i] -= delta; s1[i] -= delta; negm[i] = -mref; }
;       }
	v_add_f32_e32 v75, v91, v217
	v_add_u32_e32 v89, v177, v191
	v_add_u32_e32 v90, v177, v192
	v_add_u32_e32 v91, v177, v193
	v_add_u32_e32 v204, v177, v210
	v_add_u32_e32 v205, v177, v211
	v_add_u32_e32 v208, v177, v212
	v_add_u32_e32 v209, v177, v213
	v_add_u32_e32 v217, v177, v214
	ds_read_b32 v89, v89 offset:45984
	ds_read_b32 v90, v90 offset:45984
	ds_read_b32 v91, v91 offset:45984
	ds_read_b32 v204, v204 offset:45984
	ds_read_b32 v205, v205 offset:45984
	ds_read_b32 v208, v208 offset:45984
	ds_read_b32 v209, v209 offset:45984
	ds_read_b32 v218, v217 offset:45984
	s_waitcnt lgkmcnt(7)
	v_add_f32_e32 v76, v76, v89
	v_cndmask_b32_e64 v0, v0, v206, s[8:9]
	v_cndmask_b32_e64 v217, v206, v76, s[58:59]
	s_waitcnt lgkmcnt(6)
	v_add_f32_e32 v76, v92, v90
	v_cndmask_b32_e64 v14, v14, v206, s[16:17]
	v_cndmask_b32_e64 v15, v206, v15, s[18:19]
	v_cndmask_b32_e64 v66, v66, v206, s[20:21]
	v_cndmask_b32_e64 v89, v206, v76, s[60:61]
	s_waitcnt lgkmcnt(5)
	v_add_f32_e32 v76, v77, v91
	v_max_f32_e32 v92, v0, v65
	v_cndmask_b32_e64 v67, v206, v67, s[22:23]
	v_cndmask_b32_e64 v90, v206, v76, s[62:63]
	s_waitcnt lgkmcnt(4)
	v_add_f32_e32 v76, v93, v204
	v_max3_f32 v93, v64, v80, v15
	v_max3_f32 v92, v92, v14, v66
	v_cndmask_b32_e64 v68, v68, v206, s[34:35]
	v_cndmask_b32_e64 v69, v206, v69, s[36:37]
	v_cndmask_b32_e64 v70, v70, v206, s[38:39]
	v_max3_f32 v93, v93, v67, v82
	v_max3_f32 v92, v92, v81, v83
	v_cndmask_b32_e64 v71, v206, v71, s[40:41]
	v_max3_f32 v93, v93, v84, v69
	v_max3_f32 v92, v92, v68, v70
	v_cndmask_b32_e64 v72, v206, v72, s[50:51]
	v_cndmask_b32_e64 v73, v206, v73, s[52:53]
	v_cndmask_b32_e64 v74, v206, v74, s[54:55]
	v_cndmask_b32_e64 v91, v206, v76, s[64:65]
	s_waitcnt lgkmcnt(3)
	v_add_f32_e32 v76, v78, v205
	v_max3_f32 v93, v93, v71, v86
	v_max3_f32 v92, v92, v85, v87
	v_cndmask_b32_e64 v75, v206, v75, s[56:57]
	v_cndmask_b32_e64 v77, v206, v76, s[66:67]
	s_waitcnt lgkmcnt(2)
	v_add_f32_e32 v76, v94, v208
	s_waitcnt lgkmcnt(1)
	v_add_f32_e32 v78, v79, v209
	v_max3_f32 v93, v93, v88, v73
	v_max3_f32 v92, v92, v72, v74
	v_cndmask_b32_e64 v76, v206, v76, s[68:69]
	v_cndmask_b32_e64 v79, v206, v78, s[70:71]
	s_waitcnt lgkmcnt(0)
	v_add_f32_e32 v78, v95, v218
	v_max3_f32 v93, v93, v75, v89
	v_max3_f32 v92, v92, v217, v90
	v_cndmask_b32_e64 v78, v206, v78, s[72:73]
	v_max3_f32 v93, v93, v91, v76
	v_max3_f32 v92, v92, v77, v79
	v_max3_f32 v92, v92, v78, v93
	v_mov_b32_e32 v93, v92
	s_nop 1
	v_permlane32_swap_b32_e32 v92, v93
	v_max_f32_e32 v93, v93, v93
	v_max_f32_e32 v92, v92, v92
	v_max_f32_e32 v92, v92, v93
	v_cmp_lt_f32_e32 vcc, v234, v92
	s_cbranch_vccz .LBB0_215
	v_and_b32_e32 v93, 1, v216
	v_cmp_eq_u32_e64 s[76:77], 1, v93
	v_cmp_nlt_f32_e64 s[74:75], s33, v92
	s_nop 0
	v_max_f32_e32 v48, v92, v92
	v_max_f32_e32 v48, 0, v48
	v_exp_f32_e64 v49, -v48
	v_cndmask_b32_e64 v50, v92, 0, s[74:75]
	v_cndmask_b32_e64 v51, v50, v48, s[76:77]
	v_add_f32_e32 v215, v215, v51
	s_or_b64 vcc, s[74:75], s[76:77]
	v_cndmask_b32_e64 v50, 1.0, v49, s[76:77]
	v_xor_b32_e32 v48, 0x80000000, v215
	v_cndmask_b32_e32 v216, 1, v216, vcc
	v_and_b32_e32 v235, 1, v216
	v_cmp_eq_u32_e32 vcc, 1, v235
	v_mov_b32_e32 v235, 0x41000000
	v_mov_b32_e32 v236, 0xefa18f08
	v_cndmask_b32_e32 v234, v236, v235, vcc
	v_mul_f32_e32 v174, v174, v50
	v_sub_f32_e32 v0, v0, v51
	v_sub_f32_e32 v64, v64, v51
	v_sub_f32_e32 v65, v65, v51
	v_sub_f32_e32 v80, v80, v51
	v_sub_f32_e32 v14, v14, v51
	v_sub_f32_e32 v15, v15, v51
	v_sub_f32_e32 v66, v66, v51
	v_sub_f32_e32 v67, v67, v51
	v_sub_f32_e32 v81, v81, v51
	v_sub_f32_e32 v82, v82, v51
	v_sub_f32_e32 v83, v83, v51
	v_sub_f32_e32 v84, v84, v51
	v_sub_f32_e32 v68, v68, v51
	v_sub_f32_e32 v69, v69, v51
	v_sub_f32_e32 v70, v70, v51
	v_sub_f32_e32 v71, v71, v51
	v_sub_f32_e32 v85, v85, v51
	v_sub_f32_e32 v86, v86, v51
	v_sub_f32_e32 v87, v87, v51
	v_sub_f32_e32 v88, v88, v51
	v_sub_f32_e32 v72, v72, v51
	v_sub_f32_e32 v73, v73, v51
	v_sub_f32_e32 v74, v74, v51
	v_sub_f32_e32 v75, v75, v51
	v_sub_f32_e32 v217, v217, v51
	v_sub_f32_e32 v89, v89, v51
	v_sub_f32_e32 v90, v90, v51
	v_sub_f32_e32 v91, v91, v51
	v_sub_f32_e32 v77, v77, v51
	v_sub_f32_e32 v76, v76, v51
	v_pk_mul_f32 v[46:47], v[46:47], v[50:51] op_sel_hi:[1,0]
	v_pk_mul_f32 v[44:45], v[44:45], v[50:51] op_sel_hi:[1,0]
	v_pk_mul_f32 v[42:43], v[42:43], v[50:51] op_sel_hi:[1,0]
	v_pk_mul_f32 v[40:41], v[40:41], v[50:51] op_sel_hi:[1,0]
	v_pk_mul_f32 v[38:39], v[38:39], v[50:51] op_sel_hi:[1,0]
	v_pk_mul_f32 v[36:37], v[36:37], v[50:51] op_sel_hi:[1,0]
	v_pk_mul_f32 v[34:35], v[34:35], v[50:51] op_sel_hi:[1,0]
	v_pk_mul_f32 v[32:33], v[32:33], v[50:51] op_sel_hi:[1,0]
	v_pk_mul_f32 v[30:31], v[30:31], v[50:51] op_sel_hi:[1,0]
	v_pk_mul_f32 v[28:29], v[28:29], v[50:51] op_sel_hi:[1,0]
	v_pk_mul_f32 v[26:27], v[26:27], v[50:51] op_sel_hi:[1,0]
	v_pk_mul_f32 v[24:25], v[24:25], v[50:51] op_sel_hi:[1,0]
	v_pk_mul_f32 v[22:23], v[22:23], v[50:51] op_sel_hi:[1,0]
	v_pk_mul_f32 v[20:21], v[20:21], v[50:51] op_sel_hi:[1,0]
	v_pk_mul_f32 v[18:19], v[18:19], v[50:51] op_sel_hi:[1,0]
	v_pk_mul_f32 v[16:17], v[16:17], v[50:51] op_sel_hi:[1,0]
	v_sub_f32_e32 v79, v79, v51
	v_sub_f32_e32 v78, v78, v51
	v_mov_b32_e32 v49, v48
	v_mov_b32_e32 v50, v48
	v_mov_b32_e32 v51, v48
	v_mov_b32_e32 v52, v48
	v_mov_b32_e32 v53, v48
	v_mov_b32_e32 v54, v48
	v_mov_b32_e32 v55, v48
	v_mov_b32_e32 v56, v48
	v_mov_b32_e32 v57, v48
	v_mov_b32_e32 v58, v48
	v_mov_b32_e32 v59, v48
	v_mov_b32_e32 v60, v48
	v_mov_b32_e32 v61, v48
	v_mov_b32_e32 v62, v48
	v_mov_b32_e32 v63, v48

; DI f32x16 mfma(bf16x8 a, bf16x8 b, f32x16 c) { return __builtin_amdgcn_mfma_f32_32x32x16_bf16(a, b, c, 0, 0, 0); }
; template <int MODE>
; DI void attn_tile(const Params& p, int layer, int tile, char* smem) {
;     ...
;     if (MODE == 2) active = (kt >= rs) && (kt < rs + 8);
;     if (active) {
;       const u16* Kb = Ks + buf * 64 * KROW + r * KROW + 8 * h;
;       const u16* Vb = Vs + buf * 64 * VROW;
;       bf16x8 vf[8];
; #pragma unroll
;       for (int cs2 = 0; cs2 < 4; ++cs2) {
;         const u16* vp = Vb + (16 * cs2 + 4 * h + qq) * VROW + 16 * g16 + 4 * pp4;
;         { s16x4 lo = tr_read(vp), hi = tr_read(vp + 8 * VROW); vf[2 * cs2] = __builtin_shufflevector(lo, hi, 0, 1, 2, 3, 4, 5, 6, 7); }
;         { s16x4 lo = tr_read(vp + 32), hi = tr_read(vp + 8 * VROW + 32); vf[2 * cs2 + 1] = __builtin_shufflevector(lo, hi, 0, 1, 2, 3, 4, 5, 6, 7); }
;       }
;       f32x16 s0 = negm, s1 = negm;
; #pragma unroll
;       for (int d0 = 0; d0 < NKQ; ++d0) {
;         bf16x8 k0 = *(const bf16x8*)(Kb + d0 * 16);
;         bf16x8 k1 = *(const bf16x8*)(Kb + 32 * KROW + d0 * 16);
;         s0 = mfma(k0, qf[d0], s0);
;         s1 = mfma(k1, qf[d0], s1);
;       }
;       if (MODE == 0) {
;         const float* tb = tbl + (kt * 64 + 4 * h - qpos + 1280);
; #pragma unroll
;         for (int i = 0; i < 16; ++i) { s0[i] += tb[(i & 3) + 8 * (i >> 2)]; s1[i] += tb[32 + (i & 3) + 8 * (i >> 2)]; }
;       }
;       if (MODE == 2) {
;         const float* tb = tbl + (kt - qr + 7) * 31 + (15 - qc);
; #pragma unroll
;         for (int i = 0; i < 16; ++i) {
;           const int kc0 = 4 * h + (i & 3) + 8 * (i >> 2), kc1 = kc0 + 32;
;           const bool v0 = (kc0 >= cs) && (kc0 < cs + 16), v1 = (kc1 >= cs) && (kc1 < cs + 16);
;           const float b0 = tb[v0 ? kc0 : qc], b1 = tb[v1 ? kc1 : qc];
;           s0[i] = v0 ? s0[i] + b0 : NEGBIG;
;           s1[i] = v1 ? s1[i] + b1 : NEGBIG;
;         }
;     ...
;     lstore(rk0, rv0, 1);
;     gload(rk0, rv0, kt0 + j + 3);
;     __syncthreads();
;     if (j + 1 >= ntile) break;
;     compute(1, kt0 + j + 1);
;     lstore(rk1, rv1, 0);
;     gload(rk1, rv1, kt0 + j + 4);
;     __syncthreads();
.LBB0_218:
	s_or_b64 exec, exec, s[0:1]
	s_add_i32 s0, s82, 3
	s_min_i32 s0, s0, s86
	s_mul_i32 s0, s0, 0x26800
	v_add_u32_e32 v0, s0, v158
	s_waitcnt vmcnt(0)
	ds_write_b128 v164, v[116:119] offset:35840
	v_lshl_add_u64 v[2:3], v[0:1], 1, s[92:93]
	v_add_u32_e32 v0, s0, v156
	v_lshl_add_u64 v[4:5], v[0:1], 1, s[4:5]
	global_load_dwordx4 v[112:115], v[2:3], off
	global_load_dwordx4 v[116:119], v[4:5], off
	s_add_i32 s0, s87, 1
	s_cmp_ge_i32 s0, s83
	s_mov_b64 s[0:1], -1
	s_waitcnt lgkmcnt(0)
	s_barrier
	s_cbranch_scc1 .LBB0_211
	s_add_i32 s0, s82, 1
	v_cmp_ge_i32_e32 vcc, s0, v159
	v_cmp_lt_i32_e64 s[74:75], s0, v160
	s_and_b64 s[74:75], vcc, s[74:75]
	s_and_saveexec_b64 s[0:1], s[74:75]
	s_cbranch_execz .LBB0_223
	ds_read_b128 v[2:5], v162 offset:9216
	ds_read_b128 v[6:9], v162 offset:9248
	v_add_u32_e32 v0, v177, v165
	v_add_u32_e32 v14, v177, v166
	v_add_u32_e32 v15, v177, v167
	s_waitcnt lgkmcnt(1)
	v_mfma_f32_32x32x16_bf16 v[64:79], v[2:5], v[96:99], v[48:63]
	ds_read_b128 v[2:5], v162 offset:13824
	ds_read_b128 v[10:13], v162 offset:13856
	ds_read_b128 v[132:135], v162 offset:9280
	v_add_u32_e32 v204, v177, v168
	v_add_u32_e32 v205, v177, v169
	v_add_u32_e32 v208, v177, v170
	v_add_u32_e32 v209, v177, v171
	v_add_u32_e32 v217, v177, v172
	s_waitcnt lgkmcnt(2)
	v_mfma_f32_32x32x16_bf16 v[80:95], v[2:5], v[96:99], v[48:63]
	s_waitcnt lgkmcnt(1)
	v_mfma_f32_32x32x16_bf16 v[80:95], v[10:13], v[100:103], v[80:95]
	v_mfma_f32_32x32x16_bf16 v[64:79], v[6:9], v[100:103], v[64:79]
	ds_read_b64_tr_b16 v[128:129], v161 offset:35840
	ds_read_b64_tr_b16 v[130:131], v161 offset:36992
	ds_read_b64_tr_b16 v[12:13], v161 offset:37056
	ds_read_b64_tr_b16 v[10:11], v161 offset:35904
	ds_read_b64_tr_b16 v[6:7], v161 offset:38144
	ds_read_b64_tr_b16 v[8:9], v161 offset:39296
	ds_read_b64_tr_b16 v[4:5], v161 offset:39360
	ds_read_b64_tr_b16 v[2:3], v161 offset:38208
	ds_read_b128 v[218:221], v162 offset:13888
	ds_read_b128 v[222:225], v162 offset:9312
	s_waitcnt lgkmcnt(1)
	v_mfma_f32_32x32x16_bf16 v[80:95], v[218:221], v[104:107], v[80:95]
	v_mfma_f32_32x32x16_bf16 v[64:79], v[132:135], v[104:107], v[64:79]
	ds_read_b64_tr_b16 v[144:145], v161 offset:40448
	ds_read_b64_tr_b16 v[146:147], v161 offset:41600
	ds_read_b64_tr_b16 v[142:143], v161 offset:41664
	ds_read_b64_tr_b16 v[140:141], v161 offset:40512
	ds_read_b64_tr_b16 v[136:137], v161 offset:42752
	ds_read_b64_tr_b16 v[138:139], v161 offset:43904
	ds_read_b64_tr_b16 v[134:135], v161 offset:43968
	ds_read_b64_tr_b16 v[132:133], v161 offset:42816
	ds_read_b128 v[226:229], v162 offset:13920
	ds_read_b32 v0, v0 offset:46108
	ds_read_b32 v14, v14 offset:46108
	ds_read_b32 v15, v15 offset:46108
	ds_read_b32 v204, v204 offset:46108
	ds_read_b32 v205, v205 offset:46108
	ds_read_b32 v208, v208 offset:46108
	ds_read_b32 v209, v209 offset:46108
	ds_read_b32 v217, v217 offset:46108
	s_waitcnt lgkmcnt(8)
	v_mfma_f32_32x32x16_bf16 v[80:95], v[226:229], v[108:111], v[80:95]
	v_mfma_f32_32x32x16_bf16 v[64:79], v[222:225], v[108:111], v[64:79]
	s_waitcnt lgkmcnt(6)
	s_nop 9
	v_add_f32_e32 v14, v80, v14
	v_add_f32_e32 v0, v64, v0
	v_cndmask_b32_e64 v64, v206, v14, s[10:11]
	s_waitcnt lgkmcnt(5)
	v_add_f32_e32 v14, v65, v15
	v_cndmask_b32_e64 v65, v14, v206, s[12:13]
	s_waitcnt lgkmcnt(4)
	v_add_f32_e32 v14, v81, v204
	v_cndmask_b32_e64 v80, v206, v14, s[14:15]
	s_waitcnt lgkmcnt(3)
	v_add_f32_e32 v14, v66, v205
	s_waitcnt lgkmcnt(2)
	v_add_f32_e32 v15, v82, v208
	s_waitcnt lgkmcnt(1)
	v_add_f32_e32 v66, v67, v209
	s_waitcnt lgkmcnt(0)
	v_add_f32_e32 v67, v83, v217
	v_add_u32_e32 v81, v177, v173
	v_add_u32_e32 v82, v177, v175
	v_add_u32_e32 v83, v177, v176
	v_add_u32_e32 v204, v177, v178
	v_add_u32_e32 v205, v177, v179
	v_add_u32_e32 v208, v177, v180
	v_add_u32_e32 v209, v177, v181
	v_add_u32_e32 v217, v177, v182
	ds_read_b32 v81, v81 offset:46108
	ds_read_b32 v82, v82 offset:46108
	ds_read_b32 v83, v83 offset:46108
	ds_read_b32 v204, v204 offset:46108
	ds_read_b32 v205, v205 offset:46108
	ds_read_b32 v208, v208 offset:46108
	ds_read_b32 v209, v209 offset:46108
	ds_read_b32 v217, v217 offset:46108
	s_waitcnt lgkmcnt(7)
	v_add_f32_e32 v68, v68, v81
	v_cndmask_b32_e64 v81, v68, v206, s[24:25]
	s_waitcnt lgkmcnt(6)
	v_add_f32_e32 v68, v84, v82
	v_cndmask_b32_e64 v82, v206, v68, s[26:27]
	s_waitcnt lgkmcnt(5)
	v_add_f32_e32 v68, v69, v83
	v_cndmask_b32_e64 v83, v68, v206, s[28:29]
	s_waitcnt lgkmcnt(4)
	v_add_f32_e32 v68, v85, v204
	v_cndmask_b32_e64 v84, v206, v68, s[30:31]
	s_waitcnt lgkmcnt(3)
	v_add_f32_e32 v68, v70, v205
	s_waitcnt lgkmcnt(2)
	v_add_f32_e32 v69, v86, v208
	s_waitcnt lgkmcnt(1)
	v_add_f32_e32 v70, v71, v209
	s_waitcnt lgkmcnt(0)
	v_add_f32_e32 v71, v87, v217
	v_add_u32_e32 v85, v177, v183
	v_add_u32_e32 v86, v177, v184
	v_add_u32_e32 v87, v177, v185
	v_add_u32_e32 v204, v177, v186
	v_add_u32_e32 v205, v177, v187
	v_add_u32_e32 v208, v177, v188
	v_add_u32_e32 v209, v177, v189
	v_add_u32_e32 v217, v177, v190
	ds_read_b32 v85, v85 offset:46108
	ds_read_b32 v86, v86 offset:46108
	ds_read_b32 v87, v87 offset:46108
	ds_read_b32 v204, v204 offset:46108
	ds_read_b32 v205, v205 offset:46108
	ds_read_b32 v208, v208 offset:46108
	ds_read_b32 v209, v209 offset:46108
	ds_read_b32 v217, v217 offset:46108
	s_waitcnt lgkmcnt(7)
	v_add_f32_e32 v72, v72, v85
	v_cndmask_b32_e64 v85, v206, v72, s[42:43]
	s_waitcnt lgkmcnt(6)
	v_add_f32_e32 v72, v88, v86
	v_cndmask_b32_e64 v86, v206, v72, s[44:45]
	s_waitcnt lgkmcnt(5)
	v_add_f32_e32 v72, v73, v87
	v_cndmask_b32_e64 v87, v206, v72, s[46:47]
	s_waitcnt lgkmcnt(4)
	v_add_f32_e32 v72, v89, v204
	v_cndmask_b32_e64 v88, v206, v72, s[48:49]
	s_waitcnt lgkmcnt(3)
; DI float fexp2(float x) { return __builtin_amdgcn_exp2f(x); }
; template <int MODE>
; DI void attn_tile(const Params& p, int layer, int tile, char* smem) {
;     ...
;       float ma = __builtin_fmaxf(__builtin_fmaxf(s0[0], s0[1]), s0[2]), mb = __builtin_fmaxf(__builtin_fmaxf(s1[0], s1[1]), s1[2]);
; #pragma unroll
;       for (int i = 3; i < 15; i += 2) { ma = __builtin_fmaxf(__builtin_fmaxf(ma, s0[i]), s0[i + 1]); mb = __builtin_fmaxf(__builtin_fmaxf(mb, s1[i]), s1[i + 1]); }
;       float mt = __builtin_fmaxf(__builtin_fmaxf(ma, s0[15]), s1[15]);
;       mt = hmax(__builtin_fmaxf(mt, mb));
;       const bool fresh = !started && (mt > -1e29f);
;       if (__any(fresh || (started && mt > 8.f))) {
;         float delta = 0.f, al = 1.f;
;         if (fresh) { delta = mt; started = true; }
;         else if (started) { delta = __builtin_fmaxf(mt, 0.f); al = fexp2(-delta); }
;         mref += delta;
;         lsum *= al;
; #pragma unroll
;         for (int i = 0; i < 16; ++i) { o0[i] *= al; o1[i] *= al; s0[i] -= delta; s1[i] -= delta; negm[i] = -mref; }
;       }
	v_add_f32_e32 v72, v74, v205
	s_waitcnt lgkmcnt(2)
	v_add_f32_e32 v73, v90, v208
	s_waitcnt lgkmcnt(1)
	v_add_f32_e32 v74, v75, v209
	s_waitcnt lgkmcnt(0)
	v_add_f32_e32 v75, v91, v217
	v_add_u32_e32 v89, v177, v191
	v_add_u32_e32 v90, v177, v192
	v_add_u32_e32 v91, v177, v193
	v_add_u32_e32 v204, v177, v210
	v_add_u32_e32 v205, v177, v211
	v_add_u32_e32 v208, v177, v212
	v_add_u32_e32 v209, v177, v213
	v_add_u32_e32 v217, v177, v214
	ds_read_b32 v89, v89 offset:46108
	ds_read_b32 v90, v90 offset:46108
	ds_read_b32 v91, v91 offset:46108
	ds_read_b32 v204, v204 offset:46108
	ds_read_b32 v205, v205 offset:46108
	ds_read_b32 v208, v208 offset:46108
	ds_read_b32 v209, v209 offset:46108
	ds_read_b32 v218, v217 offset:46108
	s_waitcnt lgkmcnt(7)
	v_add_f32_e32 v76, v76, v89
	v_cndmask_b32_e64 v0, v0, v206, s[8:9]
	v_cndmask_b32_e64 v217, v206, v76, s[58:59]
	s_waitcnt lgkmcnt(6)
	v_add_f32_e32 v76, v92, v90
	v_cndmask_b32_e64 v14, v14, v206, s[16:17]
	v_cndmask_b32_e64 v15, v206, v15, s[18:19]
	v_cndmask_b32_e64 v66, v66, v206, s[20:21]
	v_cndmask_b32_e64 v89, v206, v76, s[60:61]
	s_waitcnt lgkmcnt(5)
	v_add_f32_e32 v76, v77, v91
	v_max_f32_e32 v92, v0, v65
	v_cndmask_b32_e64 v67, v206, v67, s[22:23]
	v_cndmask_b32_e64 v90, v206, v76, s[62:63]
	s_waitcnt lgkmcnt(4)
	v_add_f32_e32 v76, v93, v204
	v_max3_f32 v93, v64, v80, v15
	v_max3_f32 v92, v92, v14, v66
	v_cndmask_b32_e64 v68, v68, v206, s[34:35]
	v_cndmask_b32_e64 v69, v206, v69, s[36:37]
	v_cndmask_b32_e64 v70, v70, v206, s[38:39]
	v_max3_f32 v93, v93, v67, v82
	v_max3_f32 v92, v92, v81, v83
	v_cndmask_b32_e64 v71, v206, v71, s[40:41]
	v_max3_f32 v93, v93, v84, v69
	v_max3_f32 v92, v92, v68, v70
	v_cndmask_b32_e64 v72, v206, v72, s[50:51]
	v_cndmask_b32_e64 v73, v206, v73, s[52:53]
	v_cndmask_b32_e64 v74, v206, v74, s[54:55]
	v_cndmask_b32_e64 v91, v206, v76, s[64:65]
	s_waitcnt lgkmcnt(3)
	v_add_f32_e32 v76, v78, v205
	v_max3_f32 v93, v93, v71, v86
	v_max3_f32 v92, v92, v85, v87
	v_cndmask_b32_e64 v75, v206, v75, s[56:57]
	v_cndmask_b32_e64 v77, v206, v76, s[66:67]
	s_waitcnt lgkmcnt(2)
	v_add_f32_e32 v76, v94, v208
	s_waitcnt lgkmcnt(1)
	v_add_f32_e32 v78, v79, v209
	v_max3_f32 v93, v93, v88, v73
	v_max3_f32 v92, v92, v72, v74
	v_cndmask_b32_e64 v76, v206, v76, s[68:69]
	v_cndmask_b32_e64 v79, v206, v78, s[70:71]
	s_waitcnt lgkmcnt(0)
	v_add_f32_e32 v78, v95, v218
	v_max3_f32 v93, v93, v75, v89
	v_max3_f32 v92, v92, v217, v90
	v_cndmask_b32_e64 v78, v206, v78, s[72:73]
	v_max3_f32 v93, v93, v91, v76
	v_max3_f32 v92, v92, v77, v79
	v_max3_f32 v92, v92, v78, v93
	v_mov_b32_e32 v93, v92
	s_nop 1
	v_permlane32_swap_b32_e32 v92, v93
	v_max_f32_e32 v93, v93, v93
	v_max_f32_e32 v92, v92, v92
	v_max_f32_e32 v92, v92, v93
	v_cmp_lt_f32_e32 vcc, v234, v92
	s_cbranch_vccz .LBB0_222
	v_and_b32_e32 v93, 1, v216
	v_cmp_eq_u32_e64 s[76:77], 1, v93
	v_cmp_nlt_f32_e64 s[74:75], s33, v92
	s_nop 0
	v_max_f32_e32 v48, v92, v92
	v_max_f32_e32 v48, 0, v48
	v_exp_f32_e64 v49, -v48
	v_cndmask_b32_e64 v50, v92, 0, s[74:75]
	v_cndmask_b32_e64 v51, v50, v48, s[76:77]
	v_add_f32_e32 v215, v215, v51
	s_or_b64 vcc, s[74:75], s[76:77]
	v_cndmask_b32_e64 v50, 1.0, v49, s[76:77]
	v_xor_b32_e32 v48, 0x80000000, v215
	v_cndmask_b32_e32 v216, 1, v216, vcc
	v_and_b32_e32 v235, 1, v216
	v_cmp_eq_u32_e32 vcc, 1, v235
	v_mov_b32_e32 v235, 0x41000000
	v_mov_b32_e32 v236, 0xefa18f08
	v_cndmask_b32_e32 v234, v236, v235, vcc
	v_mul_f32_e32 v174, v174, v50
	v_sub_f32_e32 v0, v0, v51
	v_sub_f32_e32 v64, v64, v51
	v_sub_f32_e32 v65, v65, v51
	v_sub_f32_e32 v80, v80, v51
	v_sub_f32_e32 v14, v14, v51
	v_sub_f32_e32 v15, v15, v51
	v_sub_f32_e32 v66, v66, v51
	v_sub_f32_e32 v67, v67, v51
	v_sub_f32_e32 v81, v81, v51
	v_sub_f32_e32 v82, v82, v51
	v_sub_f32_e32 v83, v83, v51
	v_sub_f32_e32 v84, v84, v51
	v_sub_f32_e32 v68, v68, v51
	v_sub_f32_e32 v69, v69, v51
	v_sub_f32_e32 v70, v70, v51
	v_sub_f32_e32 v71, v71, v51
	v_sub_f32_e32 v85, v85, v51
	v_sub_f32_e32 v86, v86, v51
	v_sub_f32_e32 v87, v87, v51
	v_sub_f32_e32 v88, v88, v51
	v_sub_f32_e32 v72, v72, v51
	v_sub_f32_e32 v73, v73, v51
	v_sub_f32_e32 v74, v74, v51
	v_sub_f32_e32 v75, v75, v51
	v_sub_f32_e32 v217, v217, v51
	v_sub_f32_e32 v89, v89, v51
	v_sub_f32_e32 v90, v90, v51
	v_sub_f32_e32 v91, v91, v51
	v_sub_f32_e32 v77, v77, v51
	v_sub_f32_e32 v76, v76, v51
	v_pk_mul_f32 v[46:47], v[46:47], v[50:51] op_sel_hi:[1,0]
	v_pk_mul_f32 v[44:45], v[44:45], v[50:51] op_sel_hi:[1,0]
	v_pk_mul_f32 v[42:43], v[42:43], v[50:51] op_sel_hi:[1,0]
	v_pk_mul_f32 v[40:41], v[40:41], v[50:51] op_sel_hi:[1,0]
	v_pk_mul_f32 v[38:39], v[38:39], v[50:51] op_sel_hi:[1,0]
	v_pk_mul_f32 v[36:37], v[36:37], v[50:51] op_sel_hi:[1,0]
	v_pk_mul_f32 v[34:35], v[34:35], v[50:51] op_sel_hi:[1,0]
	v_pk_mul_f32 v[32:33], v[32:33], v[50:51] op_sel_hi:[1,0]
	v_pk_mul_f32 v[30:31], v[30:31], v[50:51] op_sel_hi:[1,0]
	v_pk_mul_f32 v[28:29], v[28:29], v[50:51] op_sel_hi:[1,0]
	v_pk_mul_f32 v[26:27], v[26:27], v[50:51] op_sel_hi:[1,0]
	v_pk_mul_f32 v[24:25], v[24:25], v[50:51] op_sel_hi:[1,0]
	v_pk_mul_f32 v[22:23], v[22:23], v[50:51] op_sel_hi:[1,0]
	v_pk_mul_f32 v[20:21], v[20:21], v[50:51] op_sel_hi:[1,0]
	v_pk_mul_f32 v[18:19], v[18:19], v[50:51] op_sel_hi:[1,0]
	v_pk_mul_f32 v[16:17], v[16:17], v[50:51] op_sel_hi:[1,0]
	v_sub_f32_e32 v79, v79, v51
	v_sub_f32_e32 v78, v78, v51
	v_mov_b32_e32 v49, v48
	v_mov_b32_e32 v50, v48
	v_mov_b32_e32 v51, v48
	v_mov_b32_e32 v52, v48
	v_mov_b32_e32 v53, v48
	v_mov_b32_e32 v54, v48
	v_mov_b32_e32 v55, v48
	v_mov_b32_e32 v56, v48
	v_mov_b32_e32 v57, v48
	v_mov_b32_e32 v58, v48
	v_mov_b32_e32 v59, v48
	v_mov_b32_e32 v60, v48
	v_mov_b32_e32 v61, v48
	v_mov_b32_e32 v62, v48
	v_mov_b32_e32 v63, v48
